# PV sections: also the first V-fragment batch is waited per consumer (counted lgkmcnt) where no older LDS op is outstanding
# baseline (speedup 1.0000x reference)
; #define SBAR() __builtin_amdgcn_sched_barrier(0)
; template <int OFF> __device__ __forceinline__ s16x4 tr_read(int vb) { s16x4 r; asm volatile("ds_read_b64_tr_b16 %0, %1 offset:%2" : "=&v"(r) : "v"(vb), "i"(OFF) : "memory"); return r; }
; template <int D0> __device__ __forceinline__ void pv_one(f32x16& od, int vb, bf16x8 pa0, bf16x8 pa1, bf16x8 pa2, bf16x8 pa3) {
;   const s16x4 l0 = tr_read<v_rd_off(D0, 0, 0)>(vb), h0 = tr_read<v_rd_off(D0, 0, 1)>(vb), l1 = tr_read<v_rd_off(D0, 1, 0)>(vb), h1 = tr_read<v_rd_off(D0, 1, 1)>(vb);
;   const s16x4 l2 = tr_read<v_rd_off(D0, 2, 0)>(vb), h2 = tr_read<v_rd_off(D0, 2, 1)>(vb), l3 = tr_read<v_rd_off(D0, 3, 0)>(vb), h3 = tr_read<v_rd_off(D0, 3, 1)>(vb);
;   asm volatile("s_waitcnt lgkmcnt(0)" ::: "memory"); SBAR();
; template <int DQK>
; __device__ __forceinline__ void partialSM(f32x16& p0, f32x16& p1, float& m_reg, float& mn, float& alpha) {
;     ...
;   if (__builtin_expect(__all(pmax - m_reg <= THR / SCALE), 1)) { mn = m_reg; alpha = 1.f; }
;   else { mn = fmaxf(m_reg, pmax); alpha = __builtin_amdgcn_exp2f((m_reg - mn) * C); m_reg = mn; }
;   const float mnC = -mn * C;
; #pragma unroll
;   for (int r = 0; r < 16; ++r) p0[r] = fmaf(p0[r], C, mnC);
; #pragma unroll
;   for (int r = 0; r < 16; ++r) p1[r] = fmaf(p1[r], C, mnC);
; #pragma unroll
;   for (int r = 0; r < 16; ++r) p0[r] = __builtin_amdgcn_exp2f(p0[r]);
; }
; __device__ __forceinline__ void finishSM(f32x16& p0, f32x16& p1, float alpha, float& l_reg, bf16x8& pa0, bf16x8& pa1, bf16x8& pa2, bf16x8& pa3) {
; #pragma unroll
;   for (int r = 0; r < 16; ++r) p1[r] = __builtin_amdgcn_exp2f(p1[r]);
;   float ps = 0;
; #pragma unroll
;   for (int r = 0; r < 16; ++r) ps += p0[r];
; #pragma unroll
;   for (int r = 0; r < 16; ++r) ps += p1[r];
;   { auto rr = __builtin_amdgcn_permlane32_swap(__float_as_uint(ps), __float_as_uint(ps), false, false);
;     ps = __uint_as_float(rr[0]) + __uint_as_float(rr[1]); }
;   l_reg = l_reg * alpha + ps;
;   pack_p(p0, p1, pa0, pa1, pa2, pa3);
; }
.LBB0_833:
	v_cndmask_b32_e64 v205, v207, v205, s[6:7]
	s_barrier
	v_mul_f32_e32 v207, 0xbdd53b94, v205
	v_fmamk_f32 v82, v82, 0x3dd53b94, v207
	v_fmamk_f32 v83, v83, 0x3dd53b94, v207
	v_fmamk_f32 v84, v84, 0x3dd53b94, v207
	v_fmamk_f32 v85, v85, 0x3dd53b94, v207
	v_fmamk_f32 v86, v86, 0x3dd53b94, v207
	v_fmamk_f32 v87, v87, 0x3dd53b94, v207
	v_fmamk_f32 v88, v88, 0x3dd53b94, v207
	v_fmamk_f32 v89, v89, 0x3dd53b94, v207
	v_fmamk_f32 v90, v90, 0x3dd53b94, v207
	v_fmamk_f32 v91, v91, 0x3dd53b94, v207
	v_fmamk_f32 v92, v92, 0x3dd53b94, v207
	v_fmamk_f32 v93, v93, 0x3dd53b94, v207
	v_fmamk_f32 v94, v94, 0x3dd53b94, v207
	v_fmamk_f32 v95, v95, 0x3dd53b94, v207
	v_fmamk_f32 v96, v96, 0x3dd53b94, v207
	v_fmamk_f32 v97, v97, 0x3dd53b94, v207
	v_fmamk_f32 v66, v66, 0x3dd53b94, v207
	v_fmamk_f32 v67, v67, 0x3dd53b94, v207
	v_fmamk_f32 v68, v68, 0x3dd53b94, v207
	v_fmamk_f32 v69, v69, 0x3dd53b94, v207
	v_fmamk_f32 v70, v70, 0x3dd53b94, v207
	v_fmamk_f32 v71, v71, 0x3dd53b94, v207
	v_fmamk_f32 v72, v72, 0x3dd53b94, v207
	v_fmamk_f32 v73, v73, 0x3dd53b94, v207
	v_fmamk_f32 v74, v74, 0x3dd53b94, v207
	v_fmamk_f32 v75, v75, 0x3dd53b94, v207
	v_fmamk_f32 v76, v76, 0x3dd53b94, v207
	v_fmamk_f32 v77, v77, 0x3dd53b94, v207
	v_fmamk_f32 v78, v78, 0x3dd53b94, v207
	v_fmamk_f32 v79, v79, 0x3dd53b94, v207
	v_fmamk_f32 v80, v80, 0x3dd53b94, v207
	v_fmac_f32_e32 v207, 0x3dd53b94, v81
	v_exp_f32_e32 v81, v82
	v_exp_f32_e32 v82, v83
	v_exp_f32_e32 v83, v84
	v_exp_f32_e32 v84, v85
	v_exp_f32_e32 v85, v86
	v_exp_f32_e32 v86, v87
	v_exp_f32_e32 v87, v88
	v_exp_f32_e32 v88, v89
	v_exp_f32_e32 v89, v90
	v_exp_f32_e32 v90, v91
	v_exp_f32_e32 v91, v92
	v_exp_f32_e32 v92, v93
	v_exp_f32_e32 v93, v94
	v_exp_f32_e32 v94, v95
	v_exp_f32_e32 v95, v96
	v_exp_f32_e32 v96, v97
	v_exp_f32_e32 v97, v66
	v_add_f32_e32 v66, 0, v81
	v_add_f32_e32 v66, v82, v66
	v_add_f32_e32 v66, v83, v66
	v_add_f32_e32 v66, v84, v66
	v_add_f32_e32 v66, v85, v66
	v_add_f32_e32 v66, v86, v66
	v_add_f32_e32 v66, v87, v66
	v_add_f32_e32 v66, v88, v66
	v_add_f32_e32 v66, v89, v66
	v_add_f32_e32 v66, v90, v66
	v_add_f32_e32 v66, v91, v66
	v_add_f32_e32 v66, v92, v66
	v_add_f32_e32 v66, v93, v66
	v_exp_f32_e32 v208, v67
	v_add_f32_e32 v66, v94, v66
	v_exp_f32_e32 v209, v68
	v_add_f32_e32 v66, v95, v66
	v_exp_f32_e32 v210, v69
	v_add_f32_e32 v66, v96, v66
	v_exp_f32_e32 v211, v70
	v_add_f32_e32 v66, v97, v66
	v_exp_f32_e32 v212, v71
	v_add_f32_e32 v66, v208, v66
	v_exp_f32_e32 v213, v72
	v_add_f32_e32 v66, v209, v66
	v_exp_f32_e32 v214, v73
	v_add_f32_e32 v66, v210, v66
	v_exp_f32_e32 v215, v74
	v_add_f32_e32 v66, v211, v66
	v_exp_f32_e32 v216, v75
	v_add_f32_e32 v66, v212, v66
	v_exp_f32_e32 v217, v76
	v_add_f32_e32 v66, v213, v66
	v_exp_f32_e32 v218, v77
	v_add_f32_e32 v66, v214, v66
	v_exp_f32_e32 v219, v78
	v_add_f32_e32 v66, v215, v66
	v_exp_f32_e32 v220, v79
	v_add_f32_e32 v66, v216, v66
	v_exp_f32_e32 v221, v80
	v_add_f32_e32 v66, v217, v66
	v_exp_f32_e32 v207, v207
	v_add_f32_e32 v66, v218, v66
	v_add_f32_e32 v66, v219, v66
	v_add_f32_e32 v66, v220, v66
	v_add_f32_e32 v66, v221, v66
	v_add_f32_e32 v66, v207, v66
	v_mov_b32_e32 v67, v66
	s_nop 1
	v_permlane32_swap_b32_e32 v66, v67
	v_cvt_pk_bf16_f32 v68, v81, v82
	v_cvt_pk_bf16_f32 v69, v83, v84
	v_cvt_pk_bf16_f32 v70, v85, v86
	v_cvt_pk_bf16_f32 v71, v87, v88
	v_cvt_pk_bf16_f32 v72, v89, v90
	v_cvt_pk_bf16_f32 v73, v91, v92
	v_cvt_pk_bf16_f32 v74, v93, v94
	v_cvt_pk_bf16_f32 v75, v95, v96
	v_cvt_pk_bf16_f32 v76, v97, v208
	v_cvt_pk_bf16_f32 v77, v209, v210
	v_cvt_pk_bf16_f32 v78, v211, v212
	v_cvt_pk_bf16_f32 v79, v213, v214
	v_cvt_pk_bf16_f32 v80, v215, v216
	v_cvt_pk_bf16_f32 v81, v217, v218
	v_cvt_pk_bf16_f32 v82, v219, v220
	v_cvt_pk_bf16_f32 v83, v221, v207
	v_permlane32_swap_b32_e32 v68, v70
	v_permlane32_swap_b32_e32 v69, v71
	v_permlane32_swap_b32_e32 v72, v74
	v_permlane32_swap_b32_e32 v73, v75
	v_permlane32_swap_b32_e32 v76, v78
	v_permlane32_swap_b32_e32 v77, v79
	v_permlane32_swap_b32_e32 v80, v82
	v_permlane32_swap_b32_e32 v81, v83
	v_lshl_add_u32 v96, s42, 14, v204
	s_setprio 1
	ds_read_b64_tr_b16 v[84:85], v96 offset:0
	ds_read_b64_tr_b16 v[86:87], v96 offset:0x800
	ds_read_b64_tr_b16 v[88:89], v96 offset:0x1000
	ds_read_b64_tr_b16 v[90:91], v96 offset:0x1800
	ds_read_b64_tr_b16 v[92:93], v96 offset:0x2000
	ds_read_b64_tr_b16 v[94:95], v96 offset:0x2800
	ds_read_b64_tr_b16 v[208:209], v96 offset:0x3000
	ds_read_b64_tr_b16 v[210:211], v96 offset:0x3800
	s_nop 0
	s_waitcnt lgkmcnt(6)
; #define SBAR() __builtin_amdgcn_sched_barrier(0)
; template <int OFF> __device__ __forceinline__ s16x4 tr_read(int vb) { s16x4 r; asm volatile("ds_read_b64_tr_b16 %0, %1 offset:%2" : "=&v"(r) : "v"(vb), "i"(OFF) : "memory"); return r; }
; template <int D0> __device__ __forceinline__ void pv_one(f32x16& od, int vb, bf16x8 pa0, bf16x8 pa1, bf16x8 pa2, bf16x8 pa3) {
;   const s16x4 l0 = tr_read<v_rd_off(D0, 0, 0)>(vb), h0 = tr_read<v_rd_off(D0, 0, 1)>(vb), l1 = tr_read<v_rd_off(D0, 1, 0)>(vb), h1 = tr_read<v_rd_off(D0, 1, 1)>(vb);
;   const s16x4 l2 = tr_read<v_rd_off(D0, 2, 0)>(vb), h2 = tr_read<v_rd_off(D0, 2, 1)>(vb), l3 = tr_read<v_rd_off(D0, 3, 0)>(vb), h3 = tr_read<v_rd_off(D0, 3, 1)>(vb);
;   asm volatile("s_waitcnt lgkmcnt(0)" ::: "memory"); SBAR();
;     ...
;   od = __builtin_amdgcn_mfma_f32_32x32x16_bf16(pa0, PK(l0, h0), od, 0, 0, 0);
;   od = __builtin_amdgcn_mfma_f32_32x32x16_bf16(pa1, PK(l1, h1), od, 0, 0, 0);
;   od = __builtin_amdgcn_mfma_f32_32x32x16_bf16(pa2, PK(l2, h2), od, 0, 0, 0);
;   od = __builtin_amdgcn_mfma_f32_32x32x16_bf16(pa3, PK(l3, h3), od, 0, 0, 0);
;     ...
; }
; __device__ __forceinline__ void pv_d0(f32x16* o, int vb, bf16x8 pa0, bf16x8 pa1, bf16x8 pa2, bf16x8 pa3) {
;   pv_one<0>(o[0], vb, pa0, pa1, pa2, pa3); pv_one<1>(o[1], vb, pa0, pa1, pa2, pa3); pv_one<2>(o[2], vb, pa0, pa1, pa2, pa3); pv_one<3>(o[3], vb, pa0, pa1, pa2, pa3);
; }
	v_mfma_f32_32x32x16_bf16 v[2:17], v[68:71], v[84:87], v[2:17]
	ds_read_b64_tr_b16 v[84:85], v96 offset:0x200
	ds_read_b64_tr_b16 v[86:87], v96 offset:0xa00
	s_waitcnt lgkmcnt(6)
	v_mfma_f32_32x32x16_bf16 v[2:17], v[72:75], v[88:91], v[2:17]
	ds_read_b64_tr_b16 v[88:89], v96 offset:0x1200
	ds_read_b64_tr_b16 v[90:91], v96 offset:0x1a00
	s_waitcnt lgkmcnt(6)
	v_mfma_f32_32x32x16_bf16 v[2:17], v[76:79], v[92:95], v[2:17]
	ds_read_b64_tr_b16 v[92:93], v96 offset:0x2200
	ds_read_b64_tr_b16 v[94:95], v96 offset:0x2a00
	ds_read_b64_tr_b16 v[212:213], v96 offset:0x3200
	ds_read_b64_tr_b16 v[214:215], v96 offset:0x3a00
	s_waitcnt lgkmcnt(8)
	v_mfma_f32_32x32x16_bf16 v[2:17], v[80:83], v[208:211], v[2:17]
	s_waitcnt lgkmcnt(6)
	v_mfma_f32_32x32x16_bf16 v[50:65], v[68:71], v[84:87], v[50:65]
	ds_read_b64_tr_b16 v[84:85], v96 offset:0x400
	ds_read_b64_tr_b16 v[86:87], v96 offset:0xc00
	s_waitcnt lgkmcnt(6)
	v_mfma_f32_32x32x16_bf16 v[50:65], v[72:75], v[88:91], v[50:65]
	ds_read_b64_tr_b16 v[88:89], v96 offset:0x1400
	ds_read_b64_tr_b16 v[90:91], v96 offset:0x1c00
	s_waitcnt lgkmcnt(6)
	v_mfma_f32_32x32x16_bf16 v[50:65], v[76:79], v[92:95], v[50:65]
	ds_read_b64_tr_b16 v[92:93], v96 offset:0x2400
	ds_read_b64_tr_b16 v[94:95], v96 offset:0x2c00
	ds_read_b64_tr_b16 v[208:209], v96 offset:0x3400
	ds_read_b64_tr_b16 v[210:211], v96 offset:0x3c00
	s_waitcnt lgkmcnt(8)
	v_mfma_f32_32x32x16_bf16 v[50:65], v[80:83], v[212:215], v[50:65]
	s_waitcnt lgkmcnt(6)
	v_mfma_f32_32x32x16_bf16 v[34:49], v[68:71], v[84:87], v[34:49]
	ds_read_b64_tr_b16 v[84:85], v96 offset:0x600
	ds_read_b64_tr_b16 v[86:87], v96 offset:0xe00
	s_waitcnt lgkmcnt(6)
	v_mfma_f32_32x32x16_bf16 v[34:49], v[72:75], v[88:91], v[34:49]
	ds_read_b64_tr_b16 v[88:89], v96 offset:0x1600
	ds_read_b64_tr_b16 v[90:91], v96 offset:0x1e00
	s_waitcnt lgkmcnt(6)
	v_mfma_f32_32x32x16_bf16 v[34:49], v[76:79], v[92:95], v[34:49]
	ds_read_b64_tr_b16 v[92:93], v96 offset:0x2600
	ds_read_b64_tr_b16 v[94:95], v96 offset:0x2e00
	ds_read_b64_tr_b16 v[212:213], v96 offset:0x3600
	ds_read_b64_tr_b16 v[214:215], v96 offset:0x3e00
	s_waitcnt lgkmcnt(8)
	v_mfma_f32_32x32x16_bf16 v[34:49], v[80:83], v[208:211], v[34:49]
	s_waitcnt lgkmcnt(6)
	v_mfma_f32_32x32x16_bf16 v[18:33], v[68:71], v[84:87], v[18:33]
	s_andn2_b64 vcc, exec, s[18:19]
	s_waitcnt lgkmcnt(4)
	v_mfma_f32_32x32x16_bf16 v[18:33], v[72:75], v[88:91], v[18:33]
	s_waitcnt lgkmcnt(2)
	v_mfma_f32_32x32x16_bf16 v[18:33], v[76:79], v[92:95], v[18:33]
	s_waitcnt lgkmcnt(0)
	v_mfma_f32_32x32x16_bf16 v[18:33], v[80:83], v[212:215], v[18:33]
	s_setprio 0
	s_cbranch_vccnz .LBB0_835
	s_xor_b32 s6, s42, 1
	s_lshl_b32 s7, s6, 14
	s_add_i32 s7, s7, 0
	v_add_u32_e32 v68, s7, v183
	s_lshl_b32 s6, s6, 13
	s_waitcnt vmcnt(0)
	ds_write_b128 v68, v[98:101]
	v_add_u32_e32 v68, s7, v182
	s_add_i32 s7, s7, s6
	ds_write_b128 v68, v[102:105]
	v_add3_u32 v68, s7, v184, v185
	ds_write_b128 v68, v[106:109] offset:32768
	v_add3_u32 v68, s7, v186, v187
	ds_write_b128 v68, v[110:113] offset:32768
	v_add3_u32 v68, s7, v188, v189
	ds_write_b128 v68, v[134:137] offset:32768

; #define SBAR() __builtin_amdgcn_sched_barrier(0)
; template <int OFF> __device__ __forceinline__ s16x4 tr_read(int vb) { s16x4 r; asm volatile("ds_read_b64_tr_b16 %0, %1 offset:%2" : "=&v"(r) : "v"(vb), "i"(OFF) : "memory"); return r; }
; template <int D0> __device__ __forceinline__ void pv_one(f32x16& od, int vb, bf16x8 pa0, bf16x8 pa1, bf16x8 pa2, bf16x8 pa3) {
;   const s16x4 l0 = tr_read<v_rd_off(D0, 0, 0)>(vb), h0 = tr_read<v_rd_off(D0, 0, 1)>(vb), l1 = tr_read<v_rd_off(D0, 1, 0)>(vb), h1 = tr_read<v_rd_off(D0, 1, 1)>(vb);
;   const s16x4 l2 = tr_read<v_rd_off(D0, 2, 0)>(vb), h2 = tr_read<v_rd_off(D0, 2, 1)>(vb), l3 = tr_read<v_rd_off(D0, 3, 0)>(vb), h3 = tr_read<v_rd_off(D0, 3, 1)>(vb);
;   asm volatile("s_waitcnt lgkmcnt(0)" ::: "memory"); SBAR();
; template <int DQK>
; __device__ __forceinline__ void partialSM(f32x16& p0, f32x16& p1, float& m_reg, float& mn, float& alpha) {
;     ...
;   if (__builtin_expect(__all(pmax - m_reg <= THR / SCALE), 1)) { mn = m_reg; alpha = 1.f; }
;   else { mn = fmaxf(m_reg, pmax); alpha = __builtin_amdgcn_exp2f((m_reg - mn) * C); m_reg = mn; }
;   const float mnC = -mn * C;
; #pragma unroll
;   for (int r = 0; r < 16; ++r) p0[r] = fmaf(p0[r], C, mnC);
; #pragma unroll
;   for (int r = 0; r < 16; ++r) p1[r] = fmaf(p1[r], C, mnC);
; #pragma unroll
;   for (int r = 0; r < 16; ++r) p0[r] = __builtin_amdgcn_exp2f(p0[r]);
; }
; __device__ __forceinline__ void finishSM(f32x16& p0, f32x16& p1, float alpha, float& l_reg, bf16x8& pa0, bf16x8& pa1, bf16x8& pa2, bf16x8& pa3) {
; #pragma unroll
;   for (int r = 0; r < 16; ++r) p1[r] = __builtin_amdgcn_exp2f(p1[r]);
;   float ps = 0;
; #pragma unroll
;   for (int r = 0; r < 16; ++r) ps += p0[r];
; #pragma unroll
;   for (int r = 0; r < 16; ++r) ps += p1[r];
;   { auto rr = __builtin_amdgcn_permlane32_swap(__float_as_uint(ps), __float_as_uint(ps), false, false);
;     ps = __uint_as_float(rr[0]) + __uint_as_float(rr[1]); }
;   l_reg = l_reg * alpha + ps;
;   pack_p(p0, p1, pa0, pa1, pa2, pa3);
; }
.LBB0_900:
	v_cndmask_b32_e64 v205, v207, v205, s[6:7]
	s_barrier
	v_mul_f32_e32 v207, 0xbdd53b94, v205
	v_fmamk_f32 v82, v82, 0x3dd53b94, v207
	v_fmamk_f32 v83, v83, 0x3dd53b94, v207
	v_fmamk_f32 v84, v84, 0x3dd53b94, v207
	v_fmamk_f32 v85, v85, 0x3dd53b94, v207
	v_fmamk_f32 v86, v86, 0x3dd53b94, v207
	v_fmamk_f32 v87, v87, 0x3dd53b94, v207
	v_fmamk_f32 v88, v88, 0x3dd53b94, v207
	v_fmamk_f32 v89, v89, 0x3dd53b94, v207
	v_fmamk_f32 v90, v90, 0x3dd53b94, v207
	v_fmamk_f32 v91, v91, 0x3dd53b94, v207
	v_fmamk_f32 v92, v92, 0x3dd53b94, v207
	v_fmamk_f32 v93, v93, 0x3dd53b94, v207
	v_fmamk_f32 v94, v94, 0x3dd53b94, v207
	v_fmamk_f32 v95, v95, 0x3dd53b94, v207
	v_fmamk_f32 v96, v96, 0x3dd53b94, v207
	v_fmamk_f32 v97, v97, 0x3dd53b94, v207
	v_fmamk_f32 v66, v66, 0x3dd53b94, v207
	v_fmamk_f32 v67, v67, 0x3dd53b94, v207
	v_fmamk_f32 v68, v68, 0x3dd53b94, v207
	v_fmamk_f32 v69, v69, 0x3dd53b94, v207
	v_fmamk_f32 v70, v70, 0x3dd53b94, v207
	v_fmamk_f32 v71, v71, 0x3dd53b94, v207
	v_fmamk_f32 v72, v72, 0x3dd53b94, v207
	v_fmamk_f32 v73, v73, 0x3dd53b94, v207
	v_fmamk_f32 v74, v74, 0x3dd53b94, v207
	v_fmamk_f32 v75, v75, 0x3dd53b94, v207
	v_fmamk_f32 v76, v76, 0x3dd53b94, v207
	v_fmamk_f32 v77, v77, 0x3dd53b94, v207
	v_fmamk_f32 v78, v78, 0x3dd53b94, v207
	v_fmamk_f32 v79, v79, 0x3dd53b94, v207
	v_fmamk_f32 v80, v80, 0x3dd53b94, v207
	v_fmac_f32_e32 v207, 0x3dd53b94, v81
	v_exp_f32_e32 v81, v82
	v_exp_f32_e32 v82, v83
	v_exp_f32_e32 v83, v84
	v_exp_f32_e32 v84, v85
	v_exp_f32_e32 v85, v86
	v_exp_f32_e32 v86, v87
	v_exp_f32_e32 v87, v88
	v_exp_f32_e32 v88, v89
	v_exp_f32_e32 v89, v90
	v_exp_f32_e32 v90, v91
	v_exp_f32_e32 v91, v92
	v_exp_f32_e32 v92, v93
	v_exp_f32_e32 v93, v94
	v_exp_f32_e32 v94, v95
	v_exp_f32_e32 v95, v96
	v_exp_f32_e32 v96, v97
	v_exp_f32_e32 v97, v66
	v_add_f32_e32 v66, 0, v81
	v_add_f32_e32 v66, v82, v66
	v_add_f32_e32 v66, v83, v66
	v_add_f32_e32 v66, v84, v66
	v_add_f32_e32 v66, v85, v66
	v_add_f32_e32 v66, v86, v66
	v_add_f32_e32 v66, v87, v66
	v_add_f32_e32 v66, v88, v66
	v_add_f32_e32 v66, v89, v66
	v_add_f32_e32 v66, v90, v66
	v_add_f32_e32 v66, v91, v66
	v_add_f32_e32 v66, v92, v66
	v_add_f32_e32 v66, v93, v66
	v_exp_f32_e32 v208, v67
	v_add_f32_e32 v66, v94, v66
	v_exp_f32_e32 v209, v68
	v_add_f32_e32 v66, v95, v66
	v_exp_f32_e32 v210, v69
	v_add_f32_e32 v66, v96, v66
	v_exp_f32_e32 v211, v70
	v_add_f32_e32 v66, v97, v66
	v_exp_f32_e32 v212, v71
	v_add_f32_e32 v66, v208, v66
	v_exp_f32_e32 v213, v72
	v_add_f32_e32 v66, v209, v66
	v_exp_f32_e32 v214, v73
	v_add_f32_e32 v66, v210, v66
	v_exp_f32_e32 v215, v74
	v_add_f32_e32 v66, v211, v66
	v_exp_f32_e32 v216, v75
	v_add_f32_e32 v66, v212, v66
	v_exp_f32_e32 v217, v76
	v_add_f32_e32 v66, v213, v66
	v_exp_f32_e32 v218, v77
	v_add_f32_e32 v66, v214, v66
	v_exp_f32_e32 v219, v78
	v_add_f32_e32 v66, v215, v66
	v_exp_f32_e32 v220, v79
	v_add_f32_e32 v66, v216, v66
	v_exp_f32_e32 v221, v80
	v_add_f32_e32 v66, v217, v66
	v_exp_f32_e32 v207, v207
	v_add_f32_e32 v66, v218, v66
	v_add_f32_e32 v66, v219, v66
	v_add_f32_e32 v66, v220, v66
	v_add_f32_e32 v66, v221, v66
	v_add_f32_e32 v66, v207, v66
	v_mov_b32_e32 v67, v66
	s_nop 1
	v_permlane32_swap_b32_e32 v66, v67
	v_cvt_pk_bf16_f32 v68, v81, v82
	v_cvt_pk_bf16_f32 v69, v83, v84
	v_cvt_pk_bf16_f32 v70, v85, v86
	v_cvt_pk_bf16_f32 v71, v87, v88
	v_cvt_pk_bf16_f32 v72, v89, v90
	v_cvt_pk_bf16_f32 v73, v91, v92
	v_cvt_pk_bf16_f32 v74, v93, v94
	v_cvt_pk_bf16_f32 v75, v95, v96
	v_cvt_pk_bf16_f32 v76, v97, v208
	v_cvt_pk_bf16_f32 v77, v209, v210
	v_cvt_pk_bf16_f32 v78, v211, v212
	v_cvt_pk_bf16_f32 v79, v213, v214
	v_cvt_pk_bf16_f32 v80, v215, v216
	v_cvt_pk_bf16_f32 v81, v217, v218
	v_cvt_pk_bf16_f32 v82, v219, v220
	v_cvt_pk_bf16_f32 v83, v221, v207
	v_permlane32_swap_b32_e32 v68, v70
	v_permlane32_swap_b32_e32 v69, v71
	v_permlane32_swap_b32_e32 v72, v74
	v_permlane32_swap_b32_e32 v73, v75
	v_permlane32_swap_b32_e32 v76, v78
	v_permlane32_swap_b32_e32 v77, v79
	v_permlane32_swap_b32_e32 v80, v82
	v_permlane32_swap_b32_e32 v81, v83
	v_lshl_add_u32 v96, s38, 14, v204
	s_setprio 1
	ds_read_b64_tr_b16 v[84:85], v96 offset:0
	ds_read_b64_tr_b16 v[86:87], v96 offset:0x800
	ds_read_b64_tr_b16 v[88:89], v96 offset:0x1000
	ds_read_b64_tr_b16 v[90:91], v96 offset:0x1800
	ds_read_b64_tr_b16 v[92:93], v96 offset:0x2000
	ds_read_b64_tr_b16 v[94:95], v96 offset:0x2800
	ds_read_b64_tr_b16 v[208:209], v96 offset:0x3000
	ds_read_b64_tr_b16 v[210:211], v96 offset:0x3800
	s_nop 0
	s_waitcnt lgkmcnt(6)
; #define SBAR() __builtin_amdgcn_sched_barrier(0)
; template <int OFF> __device__ __forceinline__ s16x4 tr_read(int vb) { s16x4 r; asm volatile("ds_read_b64_tr_b16 %0, %1 offset:%2" : "=&v"(r) : "v"(vb), "i"(OFF) : "memory"); return r; }
; template <int D0> __device__ __forceinline__ void pv_one(f32x16& od, int vb, bf16x8 pa0, bf16x8 pa1, bf16x8 pa2, bf16x8 pa3) {
;   const s16x4 l0 = tr_read<v_rd_off(D0, 0, 0)>(vb), h0 = tr_read<v_rd_off(D0, 0, 1)>(vb), l1 = tr_read<v_rd_off(D0, 1, 0)>(vb), h1 = tr_read<v_rd_off(D0, 1, 1)>(vb);
;   const s16x4 l2 = tr_read<v_rd_off(D0, 2, 0)>(vb), h2 = tr_read<v_rd_off(D0, 2, 1)>(vb), l3 = tr_read<v_rd_off(D0, 3, 0)>(vb), h3 = tr_read<v_rd_off(D0, 3, 1)>(vb);
;   asm volatile("s_waitcnt lgkmcnt(0)" ::: "memory"); SBAR();
;     ...
;   od = __builtin_amdgcn_mfma_f32_32x32x16_bf16(pa0, PK(l0, h0), od, 0, 0, 0);
;   od = __builtin_amdgcn_mfma_f32_32x32x16_bf16(pa1, PK(l1, h1), od, 0, 0, 0);
;   od = __builtin_amdgcn_mfma_f32_32x32x16_bf16(pa2, PK(l2, h2), od, 0, 0, 0);
;   od = __builtin_amdgcn_mfma_f32_32x32x16_bf16(pa3, PK(l3, h3), od, 0, 0, 0);
;     ...
; }
; __device__ __forceinline__ void pv_d0(f32x16* o, int vb, bf16x8 pa0, bf16x8 pa1, bf16x8 pa2, bf16x8 pa3) {
;   pv_one<0>(o[0], vb, pa0, pa1, pa2, pa3); pv_one<1>(o[1], vb, pa0, pa1, pa2, pa3); pv_one<2>(o[2], vb, pa0, pa1, pa2, pa3); pv_one<3>(o[3], vb, pa0, pa1, pa2, pa3);
; }
	v_mfma_f32_32x32x16_bf16 v[2:17], v[68:71], v[84:87], v[2:17]
	ds_read_b64_tr_b16 v[84:85], v96 offset:0x200
	ds_read_b64_tr_b16 v[86:87], v96 offset:0xa00
	s_waitcnt lgkmcnt(6)
	v_mfma_f32_32x32x16_bf16 v[2:17], v[72:75], v[88:91], v[2:17]
	ds_read_b64_tr_b16 v[88:89], v96 offset:0x1200
	ds_read_b64_tr_b16 v[90:91], v96 offset:0x1a00
	s_waitcnt lgkmcnt(6)
	v_mfma_f32_32x32x16_bf16 v[2:17], v[76:79], v[92:95], v[2:17]
	ds_read_b64_tr_b16 v[92:93], v96 offset:0x2200
	ds_read_b64_tr_b16 v[94:95], v96 offset:0x2a00
	ds_read_b64_tr_b16 v[212:213], v96 offset:0x3200
	ds_read_b64_tr_b16 v[214:215], v96 offset:0x3a00
	s_waitcnt lgkmcnt(8)
	v_mfma_f32_32x32x16_bf16 v[2:17], v[80:83], v[208:211], v[2:17]
	s_waitcnt lgkmcnt(6)
	v_mfma_f32_32x32x16_bf16 v[50:65], v[68:71], v[84:87], v[50:65]
	ds_read_b64_tr_b16 v[84:85], v96 offset:0x400
	ds_read_b64_tr_b16 v[86:87], v96 offset:0xc00
	s_waitcnt lgkmcnt(6)
	v_mfma_f32_32x32x16_bf16 v[50:65], v[72:75], v[88:91], v[50:65]
	ds_read_b64_tr_b16 v[88:89], v96 offset:0x1400
	ds_read_b64_tr_b16 v[90:91], v96 offset:0x1c00
	s_waitcnt lgkmcnt(6)
	v_mfma_f32_32x32x16_bf16 v[50:65], v[76:79], v[92:95], v[50:65]
	ds_read_b64_tr_b16 v[92:93], v96 offset:0x2400
	ds_read_b64_tr_b16 v[94:95], v96 offset:0x2c00
	ds_read_b64_tr_b16 v[208:209], v96 offset:0x3400
	ds_read_b64_tr_b16 v[210:211], v96 offset:0x3c00
	s_waitcnt lgkmcnt(8)
	v_mfma_f32_32x32x16_bf16 v[50:65], v[80:83], v[212:215], v[50:65]
	s_waitcnt lgkmcnt(6)
	v_mfma_f32_32x32x16_bf16 v[34:49], v[68:71], v[84:87], v[34:49]
	ds_read_b64_tr_b16 v[84:85], v96 offset:0x600
	ds_read_b64_tr_b16 v[86:87], v96 offset:0xe00
	s_waitcnt lgkmcnt(6)
	v_mfma_f32_32x32x16_bf16 v[34:49], v[72:75], v[88:91], v[34:49]
	ds_read_b64_tr_b16 v[88:89], v96 offset:0x1600
	ds_read_b64_tr_b16 v[90:91], v96 offset:0x1e00
	s_waitcnt lgkmcnt(6)
	v_mfma_f32_32x32x16_bf16 v[34:49], v[76:79], v[92:95], v[34:49]
	ds_read_b64_tr_b16 v[92:93], v96 offset:0x2600
	ds_read_b64_tr_b16 v[94:95], v96 offset:0x2e00
	ds_read_b64_tr_b16 v[212:213], v96 offset:0x3600
	ds_read_b64_tr_b16 v[214:215], v96 offset:0x3e00
	s_waitcnt lgkmcnt(8)
	v_mfma_f32_32x32x16_bf16 v[34:49], v[80:83], v[208:211], v[34:49]
	s_waitcnt lgkmcnt(6)
	v_mfma_f32_32x32x16_bf16 v[18:33], v[68:71], v[84:87], v[18:33]
	s_andn2_b64 vcc, exec, s[18:19]
	s_waitcnt lgkmcnt(4)
	v_mfma_f32_32x32x16_bf16 v[18:33], v[72:75], v[88:91], v[18:33]
	s_waitcnt lgkmcnt(2)
	v_mfma_f32_32x32x16_bf16 v[18:33], v[76:79], v[92:95], v[18:33]
	s_waitcnt lgkmcnt(0)
	v_mfma_f32_32x32x16_bf16 v[18:33], v[80:83], v[212:215], v[18:33]
	s_setprio 0
	s_cbranch_vccnz .LBB0_902
	s_xor_b32 s6, s38, 1
	s_lshl_b32 s7, s6, 14
	s_add_i32 s7, s7, 0
	v_add_u32_e32 v68, s7, v183
	s_lshl_b32 s6, s6, 13
	s_waitcnt vmcnt(0)
	ds_write_b128 v68, v[98:101]
	v_add_u32_e32 v68, s7, v182
	s_add_i32 s7, s7, s6
	ds_write_b128 v68, v[102:105]
	v_add3_u32 v68, s7, v184, v185
	ds_write_b128 v68, v[106:109] offset:32768
	v_add3_u32 v68, s7, v186, v187
	ds_write_b128 v68, v[110:113] offset:32768
	v_add3_u32 v68, s7, v188, v189
	ds_write_b128 v68, v[142:145] offset:32768

; template <int D0> __device__ __forceinline__ void pv_one(f32x16& od, int vb, bf16x8 pa0, bf16x8 pa1, bf16x8 pa2, bf16x8 pa3) {
;   const s16x4 l0 = tr_read<v_rd_off(D0, 0, 0)>(vb), h0 = tr_read<v_rd_off(D0, 0, 1)>(vb), l1 = tr_read<v_rd_off(D0, 1, 0)>(vb), h1 = tr_read<v_rd_off(D0, 1, 1)>(vb);
;   const s16x4 l2 = tr_read<v_rd_off(D0, 2, 0)>(vb), h2 = tr_read<v_rd_off(D0, 2, 1)>(vb), l3 = tr_read<v_rd_off(D0, 3, 0)>(vb), h3 = tr_read<v_rd_off(D0, 3, 1)>(vb);
;   asm volatile("s_waitcnt lgkmcnt(0)" ::: "memory"); SBAR();
;     ...
;   od = __builtin_amdgcn_mfma_f32_32x32x16_bf16(pa0, PK(l0, h0), od, 0, 0, 0);
;   od = __builtin_amdgcn_mfma_f32_32x32x16_bf16(pa1, PK(l1, h1), od, 0, 0, 0);
;   od = __builtin_amdgcn_mfma_f32_32x32x16_bf16(pa2, PK(l2, h2), od, 0, 0, 0);
;   od = __builtin_amdgcn_mfma_f32_32x32x16_bf16(pa3, PK(l3, h3), od, 0, 0, 0);
;     ...
; }
; __device__ __forceinline__ void pv_d0(f32x16* o, int vb, bf16x8 pa0, bf16x8 pa1, bf16x8 pa2, bf16x8 pa3) {
;   pv_one<0>(o[0], vb, pa0, pa1, pa2, pa3); pv_one<1>(o[1], vb, pa0, pa1, pa2, pa3); pv_one<2>(o[2], vb, pa0, pa1, pa2, pa3); pv_one<3>(o[3], vb, pa0, pa1, pa2, pa3);
; }
; template <int DQK>
; __device__ __forceinline__ void partialSM(f32x16& p0, f32x16& p1, float& m_reg, float& mn, float& alpha) {
;     ...
;   if (__builtin_expect(__all(pmax - m_reg <= THR / SCALE), 1)) { mn = m_reg; alpha = 1.f; }
;   else { mn = fmaxf(m_reg, pmax); alpha = __builtin_amdgcn_exp2f((m_reg - mn) * C); m_reg = mn; }
;   const float mnC = -mn * C;
; #pragma unroll
;   for (int r = 0; r < 16; ++r) p0[r] = fmaf(p0[r], C, mnC);
; #pragma unroll
;   for (int r = 0; r < 16; ++r) p1[r] = fmaf(p1[r], C, mnC);
; #pragma unroll
;   for (int r = 0; r < 16; ++r) p0[r] = __builtin_amdgcn_exp2f(p0[r]);
; }
; __device__ __forceinline__ void finishSM(f32x16& p0, f32x16& p1, float alpha, float& l_reg, bf16x8& pa0, bf16x8& pa1, bf16x8& pa2, bf16x8& pa3) {
; #pragma unroll
;   for (int r = 0; r < 16; ++r) p1[r] = __builtin_amdgcn_exp2f(p1[r]);
;   float ps = 0;
; #pragma unroll
;   for (int r = 0; r < 16; ++r) ps += p0[r];
; #pragma unroll
;   for (int r = 0; r < 16; ++r) ps += p1[r];
;   { auto rr = __builtin_amdgcn_permlane32_swap(__float_as_uint(ps), __float_as_uint(ps), false, false);
;     ps = __uint_as_float(rr[0]) + __uint_as_float(rr[1]); }
;   l_reg = l_reg * alpha + ps;
;   pack_p(p0, p1, pa0, pa1, pa2, pa3);
; }
.LBB0_913:
	v_cndmask_b32_e64 v205, v207, v205, s[6:7]
	v_mul_f32_e32 v207, 0xbdd53b94, v205
	v_fmamk_f32 v82, v82, 0x3dd53b94, v207
	v_fmamk_f32 v83, v83, 0x3dd53b94, v207
	v_fmamk_f32 v84, v84, 0x3dd53b94, v207
	v_fmamk_f32 v85, v85, 0x3dd53b94, v207
	v_fmamk_f32 v86, v86, 0x3dd53b94, v207
	v_fmamk_f32 v87, v87, 0x3dd53b94, v207
	v_fmamk_f32 v88, v88, 0x3dd53b94, v207
	v_fmamk_f32 v89, v89, 0x3dd53b94, v207
	v_fmamk_f32 v90, v90, 0x3dd53b94, v207
	v_fmamk_f32 v91, v91, 0x3dd53b94, v207
	v_fmamk_f32 v92, v92, 0x3dd53b94, v207
	v_fmamk_f32 v93, v93, 0x3dd53b94, v207
	v_fmamk_f32 v94, v94, 0x3dd53b94, v207
	v_fmamk_f32 v95, v95, 0x3dd53b94, v207
	v_fmamk_f32 v96, v96, 0x3dd53b94, v207
	v_fmamk_f32 v97, v97, 0x3dd53b94, v207
	v_fmamk_f32 v66, v66, 0x3dd53b94, v207
	v_fmamk_f32 v67, v67, 0x3dd53b94, v207
	v_fmamk_f32 v68, v68, 0x3dd53b94, v207
	v_fmamk_f32 v69, v69, 0x3dd53b94, v207
	v_fmamk_f32 v70, v70, 0x3dd53b94, v207
	v_fmamk_f32 v71, v71, 0x3dd53b94, v207
	v_fmamk_f32 v72, v72, 0x3dd53b94, v207
	v_fmamk_f32 v73, v73, 0x3dd53b94, v207
	v_fmamk_f32 v74, v74, 0x3dd53b94, v207
	v_fmamk_f32 v75, v75, 0x3dd53b94, v207
	v_fmamk_f32 v76, v76, 0x3dd53b94, v207
	v_fmamk_f32 v77, v77, 0x3dd53b94, v207
	v_fmamk_f32 v78, v78, 0x3dd53b94, v207
	v_fmamk_f32 v79, v79, 0x3dd53b94, v207
	v_fmamk_f32 v80, v80, 0x3dd53b94, v207
	v_fmac_f32_e32 v207, 0x3dd53b94, v81
	v_exp_f32_e32 v81, v82
	v_exp_f32_e32 v82, v83
	v_exp_f32_e32 v83, v84
	v_exp_f32_e32 v84, v85
	v_exp_f32_e32 v85, v86
	v_exp_f32_e32 v86, v87
	v_exp_f32_e32 v87, v88
	v_exp_f32_e32 v88, v89
	v_exp_f32_e32 v89, v90
	v_exp_f32_e32 v90, v91
	v_exp_f32_e32 v91, v92
	v_exp_f32_e32 v92, v93
	v_exp_f32_e32 v93, v94
	v_exp_f32_e32 v94, v95
	v_exp_f32_e32 v95, v96
	v_exp_f32_e32 v96, v97
	v_exp_f32_e32 v97, v66
	v_add_f32_e32 v66, 0, v81
	v_add_f32_e32 v66, v82, v66
	v_add_f32_e32 v66, v83, v66
	v_add_f32_e32 v66, v84, v66
	v_add_f32_e32 v66, v85, v66
	v_add_f32_e32 v66, v86, v66
	v_add_f32_e32 v66, v87, v66
	v_add_f32_e32 v66, v88, v66
	v_add_f32_e32 v66, v89, v66
	v_add_f32_e32 v66, v90, v66
	v_add_f32_e32 v66, v91, v66
	v_add_f32_e32 v66, v92, v66
	v_add_f32_e32 v66, v93, v66
	v_exp_f32_e32 v208, v67
	v_add_f32_e32 v66, v94, v66
	v_exp_f32_e32 v209, v68
	v_add_f32_e32 v66, v95, v66
	v_exp_f32_e32 v210, v69
	v_add_f32_e32 v66, v96, v66
	v_exp_f32_e32 v211, v70
	v_add_f32_e32 v66, v97, v66
	v_exp_f32_e32 v212, v71
	v_add_f32_e32 v66, v208, v66
	v_exp_f32_e32 v213, v72
	v_add_f32_e32 v66, v209, v66
	v_exp_f32_e32 v214, v73
	v_add_f32_e32 v66, v210, v66
	v_exp_f32_e32 v215, v74
	v_add_f32_e32 v66, v211, v66
	v_exp_f32_e32 v216, v75
	v_add_f32_e32 v66, v212, v66
	v_exp_f32_e32 v217, v76
	v_add_f32_e32 v66, v213, v66
	v_exp_f32_e32 v218, v77
	v_add_f32_e32 v66, v214, v66
	v_exp_f32_e32 v219, v78
	v_add_f32_e32 v66, v215, v66
	v_exp_f32_e32 v220, v79
	v_add_f32_e32 v66, v216, v66
	v_exp_f32_e32 v221, v80
	v_add_f32_e32 v66, v217, v66
	v_exp_f32_e32 v207, v207
	v_add_f32_e32 v66, v218, v66
	v_add_f32_e32 v66, v219, v66
	v_add_f32_e32 v66, v220, v66
	v_add_f32_e32 v66, v221, v66
	v_add_f32_e32 v66, v207, v66
	v_mov_b32_e32 v67, v66
	s_nop 1
	v_permlane32_swap_b32_e32 v66, v67
	v_cvt_pk_bf16_f32 v68, v81, v82
	v_cvt_pk_bf16_f32 v69, v83, v84
	v_cvt_pk_bf16_f32 v70, v85, v86
	v_cvt_pk_bf16_f32 v71, v87, v88
	v_cvt_pk_bf16_f32 v72, v89, v90
	v_cvt_pk_bf16_f32 v73, v91, v92
	v_cvt_pk_bf16_f32 v74, v93, v94
	v_cvt_pk_bf16_f32 v75, v95, v96
	v_cvt_pk_bf16_f32 v76, v97, v208
	v_cvt_pk_bf16_f32 v77, v209, v210
	v_cvt_pk_bf16_f32 v78, v211, v212
	v_cvt_pk_bf16_f32 v79, v213, v214
	v_cvt_pk_bf16_f32 v80, v215, v216
	v_cvt_pk_bf16_f32 v81, v217, v218
	v_cvt_pk_bf16_f32 v82, v219, v220
	v_cvt_pk_bf16_f32 v83, v221, v207
	v_permlane32_swap_b32_e32 v68, v70
	v_permlane32_swap_b32_e32 v69, v71
	v_permlane32_swap_b32_e32 v72, v74
	v_permlane32_swap_b32_e32 v73, v75
	v_permlane32_swap_b32_e32 v76, v78
	v_permlane32_swap_b32_e32 v77, v79
	v_permlane32_swap_b32_e32 v80, v82
	v_permlane32_swap_b32_e32 v81, v83
	v_lshl_add_u32 v96, s30, 14, v204
	ds_read_b64_tr_b16 v[84:85], v96 offset:0
	ds_read_b64_tr_b16 v[86:87], v96 offset:0x800
	ds_read_b64_tr_b16 v[88:89], v96 offset:0x1000
	ds_read_b64_tr_b16 v[90:91], v96 offset:0x1800
	ds_read_b64_tr_b16 v[92:93], v96 offset:0x2000
	ds_read_b64_tr_b16 v[94:95], v96 offset:0x2800
	ds_read_b64_tr_b16 v[208:209], v96 offset:0x3000
	ds_read_b64_tr_b16 v[210:211], v96 offset:0x3800
	s_nop 0
	s_waitcnt lgkmcnt(6)
	v_mfma_f32_32x32x16_bf16 v[2:17], v[68:71], v[84:87], v[2:17]
	ds_read_b64_tr_b16 v[84:85], v96 offset:0x200
	ds_read_b64_tr_b16 v[86:87], v96 offset:0xa00
	s_waitcnt lgkmcnt(6)
	v_mfma_f32_32x32x16_bf16 v[2:17], v[72:75], v[88:91], v[2:17]
	ds_read_b64_tr_b16 v[88:89], v96 offset:0x1200
	ds_read_b64_tr_b16 v[90:91], v96 offset:0x1a00
	s_waitcnt lgkmcnt(6)
	v_mfma_f32_32x32x16_bf16 v[2:17], v[76:79], v[92:95], v[2:17]
	ds_read_b64_tr_b16 v[92:93], v96 offset:0x2200
	ds_read_b64_tr_b16 v[94:95], v96 offset:0x2a00
	ds_read_b64_tr_b16 v[212:213], v96 offset:0x3200
	ds_read_b64_tr_b16 v[214:215], v96 offset:0x3a00
	s_waitcnt lgkmcnt(8)
	v_mfma_f32_32x32x16_bf16 v[2:17], v[80:83], v[208:211], v[2:17]
	s_waitcnt lgkmcnt(6)
	v_mfma_f32_32x32x16_bf16 v[50:65], v[68:71], v[84:87], v[50:65]
	ds_read_b64_tr_b16 v[84:85], v96 offset:0x400
	ds_read_b64_tr_b16 v[86:87], v96 offset:0xc00
	s_waitcnt lgkmcnt(6)
	v_mfma_f32_32x32x16_bf16 v[50:65], v[72:75], v[88:91], v[50:65]
	ds_read_b64_tr_b16 v[88:89], v96 offset:0x1400
	ds_read_b64_tr_b16 v[90:91], v96 offset:0x1c00
	s_waitcnt lgkmcnt(6)
	v_mfma_f32_32x32x16_bf16 v[50:65], v[76:79], v[92:95], v[50:65]
	ds_read_b64_tr_b16 v[92:93], v96 offset:0x2400
	ds_read_b64_tr_b16 v[94:95], v96 offset:0x2c00
	ds_read_b64_tr_b16 v[208:209], v96 offset:0x3400
	ds_read_b64_tr_b16 v[210:211], v96 offset:0x3c00
	s_waitcnt lgkmcnt(8)
	v_mfma_f32_32x32x16_bf16 v[50:65], v[80:83], v[212:215], v[50:65]
	s_waitcnt lgkmcnt(6)
	v_mfma_f32_32x32x16_bf16 v[34:49], v[68:71], v[84:87], v[34:49]
	ds_read_b64_tr_b16 v[84:85], v96 offset:0x600
	ds_read_b64_tr_b16 v[86:87], v96 offset:0xe00
	s_waitcnt lgkmcnt(6)
	v_mfma_f32_32x32x16_bf16 v[34:49], v[72:75], v[88:91], v[34:49]
	ds_read_b64_tr_b16 v[88:89], v96 offset:0x1600
	ds_read_b64_tr_b16 v[90:91], v96 offset:0x1e00
	s_waitcnt lgkmcnt(6)
	v_mfma_f32_32x32x16_bf16 v[34:49], v[76:79], v[92:95], v[34:49]
	ds_read_b64_tr_b16 v[92:93], v96 offset:0x2600
	ds_read_b64_tr_b16 v[94:95], v96 offset:0x2e00
	ds_read_b64_tr_b16 v[212:213], v96 offset:0x3600
	ds_read_b64_tr_b16 v[214:215], v96 offset:0x3e00
	s_waitcnt lgkmcnt(8)
	v_mfma_f32_32x32x16_bf16 v[34:49], v[80:83], v[208:211], v[34:49]
	s_waitcnt lgkmcnt(6)
	v_mfma_f32_32x32x16_bf16 v[18:33], v[68:71], v[84:87], v[18:33]
	s_andn2_b64 vcc, exec, s[18:19]
	s_waitcnt lgkmcnt(4)
	v_mfma_f32_32x32x16_bf16 v[18:33], v[72:75], v[88:91], v[18:33]
	s_waitcnt lgkmcnt(2)
	v_mfma_f32_32x32x16_bf16 v[18:33], v[76:79], v[92:95], v[18:33]
	s_waitcnt lgkmcnt(0)
	v_mfma_f32_32x32x16_bf16 v[18:33], v[80:83], v[212:215], v[18:33]
	s_cbranch_vccnz .LBB0_915
; #define SWRITE(b, i) do { *(bf16x8*)(V_lds + (b) * SH::V + vst0) = sr_[i].vs0; *(bf16x8*)(V_lds + (b) * SH::V + vst1) = sr_[i].vs1; \
;     _Pragma("unroll") for (int q_ = 0; q_ < KPT; ++q_) *(bf16x8*)(K_lds + (b) * SH::K + KSWZ(krow[q_], kcol[q_] * 2)) = sr_[i].ks[q_]; } while (0)
; template <int DQK, int MODE, int SDEPTH, int ldq, int ldk, int ldv, int ldo, int ldg> ...
;     ...
;       if (j + 1 < NT) { asm volatile("s_waitcnt vmcnt(0)" ::: "memory"); SWRITE(bsel ^ 1, 0); }
	s_xor_b32 s6, s30, 1
	s_lshl_b32 s7, s6, 14
	s_add_i32 s7, s7, 0
	v_add_u32_e32 v68, s7, v183
	s_lshl_b32 s6, s6, 13
	s_waitcnt vmcnt(0)
	ds_write_b128 v68, v[98:101]
	v_add_u32_e32 v68, s7, v182
	s_add_i32 s7, s7, s6
	ds_write_b128 v68, v[102:105]
	v_add3_u32 v68, s7, v184, v185
	ds_write_b128 v68, v[106:109] offset:32768
	v_add3_u32 v68, s7, v186, v187
	ds_write_b128 v68, v[110:113] offset:32768
	v_add3_u32 v68, s7, v188, v189
	ds_write_b128 v68, v[146:149] offset:32768

; __device__ __forceinline__ void finishSM(f32x16& p0, f32x16& p1, float alpha, float& l_reg, bf16x8& pa0, bf16x8& pa1, bf16x8& pa2, bf16x8& pa3) {
; #pragma unroll
;   for (int r = 0; r < 16; ++r) p1[r] = __builtin_amdgcn_exp2f(p1[r]);
;   float ps = 0;
; #pragma unroll
;   for (int r = 0; r < 16; ++r) ps += p0[r];
; #pragma unroll
;   for (int r = 0; r < 16; ++r) ps += p1[r];
;   { auto rr = __builtin_amdgcn_permlane32_swap(__float_as_uint(ps), __float_as_uint(ps), false, false);
;     ps = __uint_as_float(rr[0]) + __uint_as_float(rr[1]); }
;   l_reg = l_reg * alpha + ps;
;   pack_p(p0, p1, pa0, pa1, pa2, pa3);
; }
.LBB0_1920:
	ds_read_b128 v[66:69], v177 offset:49152
	ds_read_b128 v[82:85], v177 offset:57344
	ds_read_b128 v[86:89], v178 offset:49152
	ds_read_b128 v[204:207], v178 offset:57344
	ds_read_b128 v[90:93], v179 offset:49152
	ds_read_b128 v[208:211], v179 offset:57344
	ds_read_b128 v[94:97], v180 offset:49152
	ds_read_b128 v[212:215], v180 offset:57344
	s_waitcnt lgkmcnt(7)
	v_mfma_f32_32x32x16_bf16 v[66:81], v[66:69], v[126:129], 0
	ds_read_b128 v[188:191], v181 offset:49152
	ds_read_b128 v[216:219], v181 offset:57344
	ds_read_b128 v[220:223], v182 offset:49152
	ds_read_b128 v[226:229], v182 offset:57344
	ds_read_b128 v[230:233], v183 offset:49152
	ds_read_b128 v[234:237], v183 offset:57344
	ds_read_b128 v[238:241], v184 offset:49152
	ds_read_b128 v[242:245], v184 offset:57344
	s_waitcnt lgkmcnt(13)
	v_mfma_f32_32x32x16_bf16 v[66:81], v[86:89], v[122:125], v[66:81]
	v_exp_f32_e32 v86, v142
	v_exp_f32_e32 v87, v143
	v_exp_f32_e32 v88, v140
	v_exp_f32_e32 v89, v141
	v_exp_f32_e32 v140, v136
	v_exp_f32_e32 v141, v137
	v_exp_f32_e32 v142, v132
	s_waitcnt lgkmcnt(11)
	v_mfma_f32_32x32x16_bf16 v[66:81], v[90:93], v[118:121], v[66:81]
	v_exp_f32_e32 v90, v133
	v_exp_f32_e32 v91, v130
	v_exp_f32_e32 v92, v131
	v_exp_f32_e32 v93, v144
	v_exp_f32_e32 v143, v145
	v_exp_f32_e32 v144, v138
	v_exp_f32_e32 v145, v139
	s_waitcnt lgkmcnt(9)
	v_mfma_f32_32x32x16_bf16 v[66:81], v[94:97], v[114:117], v[66:81]
	v_add_f32_e32 v96, 0, v195
	v_add_f32_e32 v96, v196, v96
	v_add_f32_e32 v96, v197, v96
	v_add_f32_e32 v96, v198, v96
	v_add_f32_e32 v96, v199, v96
	v_add_f32_e32 v96, v201, v96
	v_add_f32_e32 v96, v200, v96
	s_waitcnt lgkmcnt(7)
	v_mfma_f32_32x32x16_bf16 v[66:81], v[188:191], v[110:113], v[66:81]
	v_add_f32_e32 v96, v202, v96
	v_add_f32_e32 v96, v159, v96
	v_add_f32_e32 v96, v160, v96
	v_add_f32_e32 v96, v161, v96
	v_add_f32_e32 v96, v163, v96
	v_add_f32_e32 v96, v162, v96
	v_add_f32_e32 v96, v192, v96
	s_waitcnt lgkmcnt(5)
	v_mfma_f32_32x32x16_bf16 v[66:81], v[220:223], v[106:109], v[66:81]
	v_add_f32_e32 v96, v193, v96
	v_add_f32_e32 v96, v194, v96
	v_add_f32_e32 v96, v86, v96
	v_add_f32_e32 v96, v87, v96
	v_add_f32_e32 v96, v88, v96
	v_add_f32_e32 v96, v89, v96
	v_add_f32_e32 v96, v140, v96
	s_waitcnt lgkmcnt(3)
	v_mfma_f32_32x32x16_bf16 v[66:81], v[230:233], v[102:105], v[66:81]
	v_add_f32_e32 v96, v141, v96
	v_add_f32_e32 v96, v142, v96
	v_add_f32_e32 v96, v90, v96
	v_add_f32_e32 v96, v91, v96
	v_add_f32_e32 v96, v92, v96
	v_exp_f32_e32 v94, v134
	v_add_f32_e32 v96, v93, v96
	s_waitcnt lgkmcnt(1)
	v_mfma_f32_32x32x16_bf16 v[66:81], v[238:241], v[98:101], v[66:81]
	v_exp_f32_e32 v95, v135
	v_add_f32_e32 v96, v143, v96
	v_add_f32_e32 v96, v144, v96
	v_add_f32_e32 v96, v145, v96
	v_add_f32_e32 v96, v94, v96
	v_add_f32_e32 v187, v95, v96
	v_mov_b32_e32 v188, v187
	v_cvt_pk_bf16_f32 v130, v195, v196
	v_cvt_pk_bf16_f32 v132, v199, v201
	v_permlane32_swap_b32_e32 v187, v188
	v_cvt_pk_bf16_f32 v131, v197, v198
	v_cvt_pk_bf16_f32 v133, v200, v202
	v_permlane32_swap_b32_e32 v130, v132
	v_cvt_pk_bf16_f32 v134, v159, v160
	v_cvt_pk_bf16_f32 v135, v161, v163
	v_cvt_pk_bf16_f32 v136, v162, v192
	v_cvt_pk_bf16_f32 v137, v193, v194
	v_cvt_pk_bf16_f32 v138, v86, v87
	v_cvt_pk_bf16_f32 v139, v88, v89
	v_cvt_pk_bf16_f32 v140, v140, v141
	v_cvt_pk_bf16_f32 v141, v142, v90
	v_cvt_pk_bf16_f32 v142, v91, v92
	v_cvt_pk_bf16_f32 v143, v93, v143
	v_cvt_pk_bf16_f32 v144, v144, v145
	v_cvt_pk_bf16_f32 v145, v94, v95
	v_permlane32_swap_b32_e32 v131, v133
	v_permlane32_swap_b32_e32 v134, v136
	v_permlane32_swap_b32_e32 v135, v137
	v_permlane32_swap_b32_e32 v138, v140
	v_permlane32_swap_b32_e32 v139, v141
	v_permlane32_swap_b32_e32 v142, v144
	v_permlane32_swap_b32_e32 v143, v145
	v_lshl_add_u64 v[158:159], v[152:153], 0, s[38:39]
	v_mfma_f32_32x32x16_bf16 v[82:97], v[82:85], v[126:129], 0
	v_add_co_u32_e32 v162, vcc, s63, v158
	v_lshl_add_u64 v[160:161], v[156:157], 0, s[38:39]
	s_nop 0
	v_addc_co_u32_e32 v163, vcc, 0, v159, vcc
	v_add_co_u32_e32 v194, vcc, s64, v158
	v_mfma_f32_32x32x16_bf16 v[82:97], v[204:207], v[122:125], v[82:97]
	s_nop 0
	v_addc_co_u32_e32 v195, vcc, 0, v159, vcc
	v_add_co_u32_e32 v198, vcc, s65, v160
	global_load_dwordx4 v[190:193], v[162:163], off
	s_nop 0
	global_load_dwordx4 v[194:197], v[194:195], off
	v_addc_co_u32_e32 v199, vcc, 0, v161, vcc
	v_lshl_add_u64 v[162:163], v[154:155], 0, s[38:39]
	v_add_co_u32_e32 v202, vcc, s65, v162
	global_load_dwordx4 v[198:201], v[198:199], off
	s_nop 0
	v_addc_co_u32_e32 v203, vcc, 0, v163, vcc
	global_load_dwordx4 v[202:205], v[202:203], off
	v_mfma_f32_32x32x16_bf16 v[82:97], v[208:211], v[118:121], v[82:97]
	v_mfma_f32_32x32x16_bf16 v[82:97], v[212:215], v[114:117], v[82:97]
	v_mfma_f32_32x32x16_bf16 v[82:97], v[216:219], v[110:113], v[82:97]
	v_mfma_f32_32x32x16_bf16 v[82:97], v[226:229], v[106:109], v[82:97]
	v_mfma_f32_32x32x16_bf16 v[82:97], v[234:237], v[102:105], v[82:97]
	s_waitcnt lgkmcnt(0)
	v_mfma_f32_32x32x16_bf16 v[82:97], v[242:245], v[98:101], v[82:97]
	ds_read_b64_tr_b16 v[206:207], v172 offset:0
	ds_read_b64_tr_b16 v[208:209], v172 offset:0x800
	ds_read_b64_tr_b16 v[210:211], v172 offset:0x1000
	ds_read_b64_tr_b16 v[212:213], v172 offset:0x1800
	ds_read_b64_tr_b16 v[214:215], v172 offset:0x2000
	ds_read_b64_tr_b16 v[216:217], v172 offset:0x2800
	ds_read_b64_tr_b16 v[218:219], v172 offset:0x3000
	ds_read_b64_tr_b16 v[220:221], v172 offset:0x3800
	s_nop 0
	s_waitcnt lgkmcnt(6)
	v_mfma_f32_32x32x16_bf16 v[2:17], v[130:133], v[206:209], v[2:17]
	ds_read_b64_tr_b16 v[206:207], v172 offset:0x200
	ds_read_b64_tr_b16 v[208:209], v172 offset:0xa00
	s_waitcnt lgkmcnt(6)
; #define SBAR() __builtin_amdgcn_sched_barrier(0)
; template <int OFF> __device__ __forceinline__ s16x4 tr_read(int vb) { s16x4 r; asm volatile("ds_read_b64_tr_b16 %0, %1 offset:%2" : "=&v"(r) : "v"(vb), "i"(OFF) : "memory"); return r; }
; template <int D0> __device__ __forceinline__ void pv_one(f32x16& od, int vb, bf16x8 pa0, bf16x8 pa1, bf16x8 pa2, bf16x8 pa3) {
;   const s16x4 l0 = tr_read<v_rd_off(D0, 0, 0)>(vb), h0 = tr_read<v_rd_off(D0, 0, 1)>(vb), l1 = tr_read<v_rd_off(D0, 1, 0)>(vb), h1 = tr_read<v_rd_off(D0, 1, 1)>(vb);
;   const s16x4 l2 = tr_read<v_rd_off(D0, 2, 0)>(vb), h2 = tr_read<v_rd_off(D0, 2, 1)>(vb), l3 = tr_read<v_rd_off(D0, 3, 0)>(vb), h3 = tr_read<v_rd_off(D0, 3, 1)>(vb);
;   asm volatile("s_waitcnt lgkmcnt(0)" ::: "memory"); SBAR();
;     ...
;   od = __builtin_amdgcn_mfma_f32_32x32x16_bf16(pa0, PK(l0, h0), od, 0, 0, 0);
;   od = __builtin_amdgcn_mfma_f32_32x32x16_bf16(pa1, PK(l1, h1), od, 0, 0, 0);
;   od = __builtin_amdgcn_mfma_f32_32x32x16_bf16(pa2, PK(l2, h2), od, 0, 0, 0);
;   od = __builtin_amdgcn_mfma_f32_32x32x16_bf16(pa3, PK(l3, h3), od, 0, 0, 0);
;     ...
; }
; __device__ __forceinline__ void pv_d0(f32x16* o, int vb, bf16x8 pa0, bf16x8 pa1, bf16x8 pa2, bf16x8 pa3) {
;   pv_one<0>(o[0], vb, pa0, pa1, pa2, pa3); pv_one<1>(o[1], vb, pa0, pa1, pa2, pa3); pv_one<2>(o[2], vb, pa0, pa1, pa2, pa3); pv_one<3>(o[3], vb, pa0, pa1, pa2, pa3);
; }
; template <int DQK>
; __device__ __forceinline__ void partialSM(f32x16& p0, f32x16& p1, float& m_reg, float& mn, float& alpha) {
;     ...
;   float pmax = p0[0];
; #pragma unroll
;   for (int r = 1; r < 16; ++r) pmax = fmaxf(pmax, p0[r]);
; #pragma unroll
;   for (int r = 0; r < 16; ++r) pmax = fmaxf(pmax, p1[r]);
;   { auto rr = __builtin_amdgcn_permlane32_swap(__float_as_uint(pmax), __float_as_uint(pmax), false, false);
;     pmax = fmaxf(__uint_as_float(rr[0]), __uint_as_float(rr[1])); }
;   if (__builtin_expect(__all(pmax - m_reg <= THR / SCALE), 1)) { mn = m_reg; alpha = 1.f; }
;   else { mn = fmaxf(m_reg, pmax); alpha = __builtin_amdgcn_exp2f((m_reg - mn) * C); m_reg = mn; }
	v_mfma_f32_32x32x16_bf16 v[2:17], v[134:137], v[210:213], v[2:17]
	ds_read_b64_tr_b16 v[210:211], v172 offset:0x1200
	ds_read_b64_tr_b16 v[212:213], v172 offset:0x1a00
	s_waitcnt lgkmcnt(6)
	v_mfma_f32_32x32x16_bf16 v[2:17], v[138:141], v[214:217], v[2:17]
	ds_read_b64_tr_b16 v[214:215], v172 offset:0x2200
	ds_read_b64_tr_b16 v[216:217], v172 offset:0x2a00
	ds_read_b64_tr_b16 v[226:227], v172 offset:0x3200
	ds_read_b64_tr_b16 v[228:229], v172 offset:0x3a00
	s_waitcnt lgkmcnt(8)
	v_mfma_f32_32x32x16_bf16 v[2:17], v[142:145], v[218:221], v[2:17]
	s_waitcnt lgkmcnt(6)
	v_mfma_f32_32x32x16_bf16 v[50:65], v[130:133], v[206:209], v[50:65]
	ds_read_b64_tr_b16 v[206:207], v172 offset:0x400
	ds_read_b64_tr_b16 v[208:209], v172 offset:0xc00
	s_waitcnt lgkmcnt(6)
	v_mfma_f32_32x32x16_bf16 v[50:65], v[134:137], v[210:213], v[50:65]
	ds_read_b64_tr_b16 v[210:211], v172 offset:0x1400
	ds_read_b64_tr_b16 v[212:213], v172 offset:0x1c00
	s_waitcnt lgkmcnt(6)
	v_mfma_f32_32x32x16_bf16 v[50:65], v[138:141], v[214:217], v[50:65]
	ds_read_b64_tr_b16 v[214:215], v172 offset:0x2400
	ds_read_b64_tr_b16 v[216:217], v172 offset:0x2c00
	ds_read_b64_tr_b16 v[218:219], v172 offset:0x3400
	ds_read_b64_tr_b16 v[220:221], v172 offset:0x3c00
	s_waitcnt lgkmcnt(8)
	v_mfma_f32_32x32x16_bf16 v[50:65], v[142:145], v[226:229], v[50:65]
	s_waitcnt lgkmcnt(6)
	v_mfma_f32_32x32x16_bf16 v[34:49], v[130:133], v[206:209], v[34:49]
	ds_read_b64_tr_b16 v[206:207], v172 offset:0x600
	ds_read_b64_tr_b16 v[208:209], v172 offset:0xe00
	s_waitcnt lgkmcnt(6)
	v_mfma_f32_32x32x16_bf16 v[34:49], v[134:137], v[210:213], v[34:49]
	ds_read_b64_tr_b16 v[210:211], v172 offset:0x1600
	ds_read_b64_tr_b16 v[212:213], v172 offset:0x1e00
	s_waitcnt lgkmcnt(6)
	v_mfma_f32_32x32x16_bf16 v[34:49], v[138:141], v[214:217], v[34:49]
	ds_read_b64_tr_b16 v[214:215], v172 offset:0x2600
	ds_read_b64_tr_b16 v[216:217], v172 offset:0x2e00
	ds_read_b64_tr_b16 v[226:227], v172 offset:0x3600
	ds_read_b64_tr_b16 v[228:229], v172 offset:0x3e00
	s_waitcnt lgkmcnt(8)
	v_mfma_f32_32x32x16_bf16 v[34:49], v[142:145], v[218:221], v[34:49]
	v_max_f32_e32 v189, v67, v67
	v_max_f32_e32 v218, v66, v66
	s_waitcnt lgkmcnt(6)
	v_mfma_f32_32x32x16_bf16 v[18:33], v[130:133], v[206:209], v[18:33]
	v_max_f32_e32 v189, v218, v189
	v_max3_f32 v189, v189, v68, v69
	v_max3_f32 v189, v189, v70, v71
	v_max3_f32 v130, v189, v72, v73
	v_max3_f32 v130, v130, v74, v75
	v_max3_f32 v130, v130, v76, v77
	v_max3_f32 v130, v130, v78, v79
	v_max3_f32 v130, v130, v80, v81
	s_waitcnt lgkmcnt(4)
	v_mfma_f32_32x32x16_bf16 v[18:33], v[134:137], v[210:213], v[18:33]
	v_max3_f32 v130, v130, v82, v83
	v_max3_f32 v130, v130, v84, v85
	v_max3_f32 v130, v130, v86, v87
	v_max3_f32 v130, v130, v88, v89
	v_max3_f32 v130, v130, v90, v91
	v_max3_f32 v130, v130, v92, v93
	v_max3_f32 v130, v130, v94, v95
	v_max3_f32 v130, v130, v96, v97
	s_waitcnt lgkmcnt(2)
	v_mfma_f32_32x32x16_bf16 v[18:33], v[138:141], v[214:217], v[18:33]
	v_mov_b32_e32 v131, v130
	s_nop 1
	v_permlane32_swap_b32_e32 v130, v131
	v_max_f32_e32 v131, v131, v131
	v_max_f32_e32 v130, v130, v130
	v_max_f32_e32 v130, v130, v131
	v_sub_f32_e32 v131, v130, v186
	v_cmp_ge_f32_e32 vcc, s60, v131
	v_max_f32_e32 v131, v186, v186
	v_max_f32_e32 v130, v131, v130
	s_waitcnt lgkmcnt(0)
	v_mfma_f32_32x32x16_bf16 v[18:33], v[142:145], v[226:229], v[18:33]
	v_sub_f32_e32 v131, v186, v130
	v_mul_f32_e32 v131, 0x3e0293ee, v131
	v_exp_f32_e32 v131, v131
	s_cmp_eq_u64 vcc, exec
	s_barrier
	s_waitcnt vmcnt(0)
	s_cselect_b64 s[6:7], -1, 0
	v_cndmask_b32_e64 v189, v131, 1.0, s[6:7]
	v_cmp_gt_f32_e32 vcc, 1.0, v189
	s_waitcnt vmcnt(3)
	ds_write_b128 v173, v[190:193]
	s_waitcnt vmcnt(2)
	ds_write_b128 v174, v[194:197]
	s_waitcnt vmcnt(1)
	ds_write_b128 v175, v[198:201] offset:32768
	s_waitcnt vmcnt(0)
	ds_write_b128 v176, v[202:205] offset:32768
	s_cbranch_vccz .LBB0_1924
	s_and_saveexec_b64 s[54:55], s[4:5]
	ds_write_b32 v168, v189 offset:128
	s_or_b64 exec, exec, s[54:55]
	s_waitcnt lgkmcnt(0)
	v_add_u32_e32 v131, v151, v146
	ds_read_b128 v[132:135], v131 offset:224
	ds_read_b128 v[136:139], v131 offset:192
	ds_read_b128 v[140:143], v131 offset:160
	ds_read_b128 v[190:193], v131 offset:128
	s_waitcnt lgkmcnt(3)
	v_pk_mul_f32 v[14:15], v[14:15], v[132:133]
	s_waitcnt lgkmcnt(2)
	v_pk_mul_f32 v[10:11], v[10:11], v[136:137]
	s_waitcnt lgkmcnt(1)
	v_pk_mul_f32 v[6:7], v[6:7], v[140:141]
	v_pk_mul_f32 v[16:17], v[16:17], v[134:135]
	v_pk_mul_f32 v[12:13], v[12:13], v[138:139]
	v_pk_mul_f32 v[8:9], v[8:9], v[142:143]
	s_waitcnt lgkmcnt(0)
	v_pk_mul_f32 v[4:5], v[4:5], v[192:193]
	v_pk_mul_f32 v[2:3], v[2:3], v[190:191]
	v_pk_mul_f32 v[62:63], v[62:63], v[132:133]
	v_pk_mul_f32 v[58:59], v[58:59], v[136:137]
	v_pk_mul_f32 v[54:55], v[54:55], v[140:141]
	v_pk_mul_f32 v[64:65], v[64:65], v[134:135]
	v_pk_mul_f32 v[60:61], v[60:61], v[138:139]
	v_pk_mul_f32 v[56:57], v[56:57], v[142:143]
	v_pk_mul_f32 v[52:53], v[52:53], v[192:193]
	v_pk_mul_f32 v[50:51], v[50:51], v[190:191]
	v_pk_mul_f32 v[46:47], v[46:47], v[132:133]
	v_pk_mul_f32 v[42:43], v[42:43], v[136:137]
	v_pk_mul_f32 v[38:39], v[38:39], v[140:141]
	v_pk_mul_f32 v[48:49], v[48:49], v[134:135]
	v_pk_mul_f32 v[44:45], v[44:45], v[138:139]
	v_pk_mul_f32 v[40:41], v[40:41], v[142:143]
	v_pk_mul_f32 v[36:37], v[36:37], v[192:193]
	v_pk_mul_f32 v[34:35], v[34:35], v[190:191]
	v_pk_mul_f32 v[30:31], v[30:31], v[132:133]
	v_pk_mul_f32 v[26:27], v[26:27], v[136:137]
	v_pk_mul_f32 v[22:23], v[22:23], v[140:141]
	v_pk_mul_f32 v[32:33], v[32:33], v[134:135]
	v_pk_mul_f32 v[28:29], v[28:29], v[138:139]
	v_pk_mul_f32 v[24:25], v[24:25], v[142:143]
	v_pk_mul_f32 v[20:21], v[20:21], v[192:193]
	v_pk_mul_f32 v[18:19], v[18:19], v[190:191]
; template <int DQK>
; __device__ __forceinline__ void partialSM(f32x16& p0, f32x16& p1, float& m_reg, float& mn, float& alpha) {
;     ...
;   const float mnC = -mn * C;
; #pragma unroll
;   for (int r = 0; r < 16; ++r) p0[r] = fmaf(p0[r], C, mnC);
; #pragma unroll
;   for (int r = 0; r < 16; ++r) p1[r] = fmaf(p1[r], C, mnC);
; #pragma unroll
;   for (int r = 0; r < 16; ++r) p0[r] = __builtin_amdgcn_exp2f(p0[r]);
; }
; __device__ __forceinline__ void finishSM(f32x16& p0, f32x16& p1, float alpha, float& l_reg, bf16x8& pa0, bf16x8& pa1, bf16x8& pa2, bf16x8& pa3) {
; #pragma unroll
;   for (int r = 0; r < 16; ++r) p1[r] = __builtin_amdgcn_exp2f(p1[r]);
;   float ps = 0;
; #pragma unroll
;   for (int r = 0; r < 16; ++r) ps += p0[r];
; #pragma unroll
;   for (int r = 0; r < 16; ++r) ps += p1[r];
;   { auto rr = __builtin_amdgcn_permlane32_swap(__float_as_uint(ps), __float_as_uint(ps), false, false);
;     ps = __uint_as_float(rr[0]) + __uint_as_float(rr[1]); }
;   l_reg = l_reg * alpha + ps;
;   pack_p(p0, p1, pa0, pa1, pa2, pa3);
; }
.LBB0_1924:
	v_cndmask_b32_e64 v130, v130, v186, s[6:7]
	v_mul_f32_e32 v142, 0xbe0293ee, v130
	v_fmamk_f32 v66, v66, 0x3e0293ee, v142
	v_fmamk_f32 v74, v74, 0x3e0293ee, v142
	v_fmamk_f32 v75, v75, 0x3e0293ee, v142
	v_fmamk_f32 v76, v76, 0x3e0293ee, v142
	v_fmamk_f32 v77, v77, 0x3e0293ee, v142
	v_fmamk_f32 v78, v78, 0x3e0293ee, v142
	v_fmamk_f32 v190, v82, 0x3e0293ee, v142
	v_fmamk_f32 v186, v84, 0x3e0293ee, v142
	v_fmamk_f32 v145, v86, 0x3e0293ee, v142
	v_fmamk_f32 v144, v88, 0x3e0293ee, v142
	v_fmamk_f32 v143, v90, 0x3e0293ee, v142
	v_exp_f32_e32 v88, v66
	v_exp_f32_e32 v82, v74
	v_exp_f32_e32 v84, v75
	v_exp_f32_e32 v86, v76
	v_exp_f32_e32 v90, v77
	v_exp_f32_e32 v131, v78
	v_fmamk_f32 v67, v67, 0x3e0293ee, v142
	v_fmamk_f32 v68, v68, 0x3e0293ee, v142
	v_fmamk_f32 v69, v69, 0x3e0293ee, v142
	v_fmamk_f32 v70, v70, 0x3e0293ee, v142
	v_fmamk_f32 v71, v71, 0x3e0293ee, v142
	v_fmamk_f32 v72, v72, 0x3e0293ee, v142
	v_fmamk_f32 v73, v73, 0x3e0293ee, v142
	v_fmamk_f32 v79, v79, 0x3e0293ee, v142
	v_fmamk_f32 v80, v80, 0x3e0293ee, v142
	v_fmamk_f32 v81, v81, 0x3e0293ee, v142
	v_fmamk_f32 v191, v92, 0x3e0293ee, v142
	v_fmamk_f32 v94, v94, 0x3e0293ee, v142
	v_fmamk_f32 v92, v96, 0x3e0293ee, v142
	v_fmamk_f32 v83, v83, 0x3e0293ee, v142
	v_fmamk_f32 v85, v85, 0x3e0293ee, v142
	v_fmamk_f32 v87, v87, 0x3e0293ee, v142
	v_fmamk_f32 v89, v89, 0x3e0293ee, v142
	v_fmamk_f32 v91, v91, 0x3e0293ee, v142
	v_fmamk_f32 v93, v93, 0x3e0293ee, v142
	v_fmamk_f32 v95, v95, 0x3e0293ee, v142
	v_exp_f32_e32 v132, v67
	v_exp_f32_e32 v133, v68
	v_exp_f32_e32 v136, v69
	v_exp_f32_e32 v137, v70
	v_exp_f32_e32 v139, v71
	v_exp_f32_e32 v140, v72
	v_exp_f32_e32 v141, v73
	v_exp_f32_e32 v134, v79
	v_exp_f32_e32 v135, v80
	v_exp_f32_e32 v138, v81
	v_fmac_f32_e32 v142, 0x3e0293ee, v97
	s_waitcnt lgkmcnt(0)
	s_barrier
	ds_read_b128 v[66:69], v177 offset:32768
	ds_read_b128 v[192:195], v177 offset:40960
	ds_read_b128 v[196:199], v178 offset:32768
	ds_read_b128 v[200:203], v178 offset:40960
	ds_read_b128 v[204:207], v179 offset:32768
	ds_read_b128 v[208:211], v179 offset:40960
	ds_read_b128 v[212:215], v180 offset:32768
	ds_read_b128 v[216:219], v180 offset:40960
	s_waitcnt lgkmcnt(7)
	v_mfma_f32_32x32x16_bf16 v[66:81], v[66:69], v[126:129], 0
	ds_read_b128 v[220:223], v181 offset:32768
	ds_read_b128 v[226:229], v181 offset:40960
	ds_read_b128 v[230:233], v182 offset:32768
	ds_read_b128 v[234:237], v182 offset:40960
	ds_read_b128 v[238:241], v183 offset:32768
	ds_read_b128 v[242:245], v183 offset:40960
	ds_read_b128 v[246:249], v184 offset:32768
	ds_read_b128 v[250:253], v184 offset:40960
	v_exp_f32_e32 v96, v190
	v_exp_f32_e32 v83, v83
	v_exp_f32_e32 v97, v186
	v_exp_f32_e32 v85, v85
	v_exp_f32_e32 v186, v145
	v_exp_f32_e32 v87, v87
	s_waitcnt lgkmcnt(13)
	v_mfma_f32_32x32x16_bf16 v[66:81], v[196:199], v[122:125], v[66:81]
	v_exp_f32_e32 v199, v142
	v_add_f32_e32 v142, 0, v88
	v_add_f32_e32 v142, v132, v142
	v_add_f32_e32 v142, v133, v142
	v_add_f32_e32 v142, v136, v142
	v_add_f32_e32 v142, v137, v142
	v_add_f32_e32 v142, v139, v142
	s_waitcnt lgkmcnt(11)
	v_mfma_f32_32x32x16_bf16 v[66:81], v[204:207], v[118:121], v[66:81]
	v_add_f32_e32 v142, v140, v142
	v_add_f32_e32 v142, v141, v142
	v_add_f32_e32 v142, v82, v142
	v_add_f32_e32 v142, v84, v142
	v_add_f32_e32 v142, v86, v142
	v_add_f32_e32 v142, v90, v142
	v_add_f32_e32 v142, v131, v142
	s_waitcnt lgkmcnt(9)
	v_mfma_f32_32x32x16_bf16 v[66:81], v[212:215], v[114:117], v[66:81]
	v_add_f32_e32 v142, v134, v142
	v_add_f32_e32 v142, v135, v142
	v_add_f32_e32 v142, v138, v142
	v_add_f32_e32 v142, v96, v142
	v_add_f32_e32 v142, v83, v142
	v_exp_f32_e32 v196, v144
	v_add_f32_e32 v142, v97, v142
	s_waitcnt lgkmcnt(7)
	v_mfma_f32_32x32x16_bf16 v[66:81], v[220:223], v[110:113], v[66:81]
	v_exp_f32_e32 v89, v89
	v_add_f32_e32 v142, v85, v142
	v_exp_f32_e32 v197, v143
	v_add_f32_e32 v142, v186, v142
	v_exp_f32_e32 v91, v91
	v_add_f32_e32 v142, v87, v142
	v_exp_f32_e32 v198, v191
	s_waitcnt lgkmcnt(5)
	v_mfma_f32_32x32x16_bf16 v[66:81], v[230:233], v[106:109], v[66:81]
	v_add_f32_e32 v142, v196, v142
	v_exp_f32_e32 v93, v93
	v_add_f32_e32 v142, v89, v142
	v_exp_f32_e32 v94, v94
	v_add_f32_e32 v142, v197, v142
	v_exp_f32_e32 v95, v95
	v_add_f32_e32 v142, v91, v142
	s_waitcnt lgkmcnt(3)
	v_mfma_f32_32x32x16_bf16 v[66:81], v[238:241], v[102:105], v[66:81]
	v_exp_f32_e32 v92, v92
	v_add_f32_e32 v142, v198, v142
	v_add_f32_e32 v142, v93, v142
	v_add_f32_e32 v142, v94, v142
	v_add_f32_e32 v142, v95, v142
	v_add_f32_e32 v142, v92, v142
	v_add_f32_e32 v190, v199, v142
	s_waitcnt lgkmcnt(1)
	v_mfma_f32_32x32x16_bf16 v[66:81], v[246:249], v[98:101], v[66:81]
	v_mov_b32_e32 v191, v190
	s_nop 1
	v_permlane32_swap_b32_e32 v190, v191
	v_cvt_pk_bf16_f32 v142, v88, v132
	v_cvt_pk_bf16_f32 v143, v133, v136
	v_cvt_pk_bf16_f32 v144, v137, v139
	v_cvt_pk_bf16_f32 v145, v140, v141
	v_cvt_pk_bf16_f32 v132, v82, v84
	v_cvt_pk_bf16_f32 v133, v86, v90
	v_cvt_pk_bf16_f32 v134, v131, v134
	v_cvt_pk_bf16_f32 v135, v135, v138
	v_cvt_pk_bf16_f32 v136, v96, v83
	v_cvt_pk_bf16_f32 v137, v97, v85
	v_cvt_pk_bf16_f32 v138, v186, v87
	v_cvt_pk_bf16_f32 v139, v196, v89
	v_cvt_pk_bf16_f32 v196, v197, v91
	v_cvt_pk_bf16_f32 v197, v198, v93
	v_cvt_pk_bf16_f32 v198, v94, v95
	v_cvt_pk_bf16_f32 v199, v92, v199
	v_permlane32_swap_b32_e32 v142, v144
	v_permlane32_swap_b32_e32 v143, v145
	v_permlane32_swap_b32_e32 v132, v134
	v_permlane32_swap_b32_e32 v133, v135
	v_permlane32_swap_b32_e32 v136, v138
	v_permlane32_swap_b32_e32 v137, v139
	v_permlane32_swap_b32_e32 v196, v198
	v_permlane32_swap_b32_e32 v197, v199
	v_mfma_f32_32x32x16_bf16 v[82:97], v[192:195], v[126:129], 0
	v_add_co_u32_e32 v140, vcc, s68, v158
	s_nop 1
	v_addc_co_u32_e32 v141, vcc, 0, v159, vcc
	v_add_co_u32_e32 v158, vcc, s69, v158
	v_mfma_f32_32x32x16_bf16 v[82:97], v[200:203], v[122:125], v[82:97]
	s_nop 0
	v_addc_co_u32_e32 v159, vcc, 0, v159, vcc
	global_load_dwordx4 v[192:195], v[140:141], off
	global_load_dwordx4 v[200:203], v[158:159], off
	v_add_co_u32_e32 v140, vcc, s70, v160
	s_nop 1
	v_addc_co_u32_e32 v141, vcc, 0, v161, vcc
	v_add_co_u32_e32 v162, vcc, s70, v162
	global_load_dwordx4 v[158:161], v[140:141], off
	s_nop 0
	v_addc_co_u32_e32 v163, vcc, 0, v163, vcc
	global_load_dwordx4 v[204:207], v[162:163], off
	v_mfma_f32_32x32x16_bf16 v[82:97], v[208:211], v[118:121], v[82:97]
	v_mfma_f32_32x32x16_bf16 v[82:97], v[216:219], v[114:117], v[82:97]
	v_mfma_f32_32x32x16_bf16 v[82:97], v[226:229], v[110:113], v[82:97]
	v_mfma_f32_32x32x16_bf16 v[82:97], v[234:237], v[106:109], v[82:97]
	v_mfma_f32_32x32x16_bf16 v[82:97], v[242:245], v[102:105], v[82:97]
	s_waitcnt lgkmcnt(0)
; #define SBAR() __builtin_amdgcn_sched_barrier(0)
; template <int OFF> __device__ __forceinline__ s16x4 tr_read(int vb) { s16x4 r; asm volatile("ds_read_b64_tr_b16 %0, %1 offset:%2" : "=&v"(r) : "v"(vb), "i"(OFF) : "memory"); return r; }
; template <int D0> __device__ __forceinline__ void pv_one(f32x16& od, int vb, bf16x8 pa0, bf16x8 pa1, bf16x8 pa2, bf16x8 pa3) {
;   const s16x4 l0 = tr_read<v_rd_off(D0, 0, 0)>(vb), h0 = tr_read<v_rd_off(D0, 0, 1)>(vb), l1 = tr_read<v_rd_off(D0, 1, 0)>(vb), h1 = tr_read<v_rd_off(D0, 1, 1)>(vb);
;   const s16x4 l2 = tr_read<v_rd_off(D0, 2, 0)>(vb), h2 = tr_read<v_rd_off(D0, 2, 1)>(vb), l3 = tr_read<v_rd_off(D0, 3, 0)>(vb), h3 = tr_read<v_rd_off(D0, 3, 1)>(vb);
;   asm volatile("s_waitcnt lgkmcnt(0)" ::: "memory"); SBAR();
;     ...
;   od = __builtin_amdgcn_mfma_f32_32x32x16_bf16(pa0, PK(l0, h0), od, 0, 0, 0);
;   od = __builtin_amdgcn_mfma_f32_32x32x16_bf16(pa1, PK(l1, h1), od, 0, 0, 0);
;   od = __builtin_amdgcn_mfma_f32_32x32x16_bf16(pa2, PK(l2, h2), od, 0, 0, 0);
;   od = __builtin_amdgcn_mfma_f32_32x32x16_bf16(pa3, PK(l3, h3), od, 0, 0, 0);
;     ...
; }
; __device__ __forceinline__ void pv_d0(f32x16* o, int vb, bf16x8 pa0, bf16x8 pa1, bf16x8 pa2, bf16x8 pa3) {
;   pv_one<0>(o[0], vb, pa0, pa1, pa2, pa3); pv_one<1>(o[1], vb, pa0, pa1, pa2, pa3); pv_one<2>(o[2], vb, pa0, pa1, pa2, pa3); pv_one<3>(o[3], vb, pa0, pa1, pa2, pa3);
; }
; template <int DQK>
; __device__ __forceinline__ void partialSM(f32x16& p0, f32x16& p1, float& m_reg, float& mn, float& alpha) {
;     ...
;   float pmax = p0[0];
; #pragma unroll
;   for (int r = 1; r < 16; ++r) pmax = fmaxf(pmax, p0[r]);
; #pragma unroll
;   for (int r = 0; r < 16; ++r) pmax = fmaxf(pmax, p1[r]);
;   { auto rr = __builtin_amdgcn_permlane32_swap(__float_as_uint(pmax), __float_as_uint(pmax), false, false);
;     pmax = fmaxf(__uint_as_float(rr[0]), __uint_as_float(rr[1])); }
;   if (__builtin_expect(__all(pmax - m_reg <= THR / SCALE), 1)) { mn = m_reg; alpha = 1.f; }
;   else { mn = fmaxf(m_reg, pmax); alpha = __builtin_amdgcn_exp2f((m_reg - mn) * C); m_reg = mn; }
	v_mfma_f32_32x32x16_bf16 v[82:97], v[250:253], v[98:101], v[82:97]
	ds_read_b64_tr_b16 v[208:209], v169 offset:0
	ds_read_b64_tr_b16 v[210:211], v169 offset:0x800
	ds_read_b64_tr_b16 v[212:213], v169 offset:0x1000
	ds_read_b64_tr_b16 v[214:215], v169 offset:0x1800
	ds_read_b64_tr_b16 v[216:217], v169 offset:0x2000
	ds_read_b64_tr_b16 v[218:219], v169 offset:0x2800
	ds_read_b64_tr_b16 v[220:221], v169 offset:0x3000
	ds_read_b64_tr_b16 v[222:223], v169 offset:0x3800
	s_nop 0
	s_waitcnt lgkmcnt(6)
	v_mfma_f32_32x32x16_bf16 v[2:17], v[142:145], v[208:211], v[2:17]
	ds_read_b64_tr_b16 v[208:209], v169 offset:0x200
	ds_read_b64_tr_b16 v[210:211], v169 offset:0xa00
	s_waitcnt lgkmcnt(6)
	v_mfma_f32_32x32x16_bf16 v[2:17], v[132:135], v[212:215], v[2:17]
	ds_read_b64_tr_b16 v[212:213], v169 offset:0x1200
	ds_read_b64_tr_b16 v[214:215], v169 offset:0x1a00
	s_waitcnt lgkmcnt(6)
	v_mfma_f32_32x32x16_bf16 v[2:17], v[136:139], v[216:219], v[2:17]
	ds_read_b64_tr_b16 v[216:217], v169 offset:0x2200
	ds_read_b64_tr_b16 v[218:219], v169 offset:0x2a00
	ds_read_b64_tr_b16 v[226:227], v169 offset:0x3200
	ds_read_b64_tr_b16 v[228:229], v169 offset:0x3a00
	s_waitcnt lgkmcnt(8)
	v_mfma_f32_32x32x16_bf16 v[2:17], v[196:199], v[220:223], v[2:17]
	s_waitcnt lgkmcnt(6)
	v_mfma_f32_32x32x16_bf16 v[50:65], v[142:145], v[208:211], v[50:65]
	ds_read_b64_tr_b16 v[208:209], v169 offset:0x400
	ds_read_b64_tr_b16 v[210:211], v169 offset:0xc00
	s_waitcnt lgkmcnt(6)
	v_mfma_f32_32x32x16_bf16 v[50:65], v[132:135], v[212:215], v[50:65]
	ds_read_b64_tr_b16 v[212:213], v169 offset:0x1400
	ds_read_b64_tr_b16 v[214:215], v169 offset:0x1c00
	s_waitcnt lgkmcnt(6)
	v_mfma_f32_32x32x16_bf16 v[50:65], v[136:139], v[216:219], v[50:65]
	ds_read_b64_tr_b16 v[216:217], v169 offset:0x2400
	ds_read_b64_tr_b16 v[218:219], v169 offset:0x2c00
	ds_read_b64_tr_b16 v[220:221], v169 offset:0x3400
	ds_read_b64_tr_b16 v[222:223], v169 offset:0x3c00
	s_waitcnt lgkmcnt(8)
	v_mfma_f32_32x32x16_bf16 v[50:65], v[196:199], v[226:229], v[50:65]
	s_waitcnt lgkmcnt(6)
	v_mfma_f32_32x32x16_bf16 v[34:49], v[142:145], v[208:211], v[34:49]
	ds_read_b64_tr_b16 v[208:209], v169 offset:0x600
	ds_read_b64_tr_b16 v[210:211], v169 offset:0xe00
	s_waitcnt lgkmcnt(6)
	v_mfma_f32_32x32x16_bf16 v[34:49], v[132:135], v[212:215], v[34:49]
	ds_read_b64_tr_b16 v[212:213], v169 offset:0x1600
	ds_read_b64_tr_b16 v[214:215], v169 offset:0x1e00
	s_waitcnt lgkmcnt(6)
	v_mfma_f32_32x32x16_bf16 v[34:49], v[136:139], v[216:219], v[34:49]
	ds_read_b64_tr_b16 v[216:217], v169 offset:0x2600
	ds_read_b64_tr_b16 v[218:219], v169 offset:0x2e00
	ds_read_b64_tr_b16 v[226:227], v169 offset:0x3600
	ds_read_b64_tr_b16 v[228:229], v169 offset:0x3e00
	s_waitcnt lgkmcnt(8)
	v_mfma_f32_32x32x16_bf16 v[34:49], v[196:199], v[220:223], v[34:49]
	v_max_f32_e32 v131, v67, v67
	v_max_f32_e32 v140, v66, v66
	s_waitcnt lgkmcnt(6)
	v_mfma_f32_32x32x16_bf16 v[18:33], v[142:145], v[208:211], v[18:33]
	v_max_f32_e32 v131, v140, v131
	v_max3_f32 v131, v131, v68, v69
	v_max3_f32 v131, v131, v70, v71
	v_max3_f32 v131, v131, v72, v73
	v_max3_f32 v131, v131, v74, v75
	v_max3_f32 v131, v131, v76, v77
	v_max3_f32 v131, v131, v78, v79
	v_max3_f32 v131, v131, v80, v81
	s_waitcnt lgkmcnt(4)
	v_mfma_f32_32x32x16_bf16 v[18:33], v[132:135], v[212:215], v[18:33]
	v_max3_f32 v131, v131, v82, v83
	v_max3_f32 v131, v131, v84, v85
	v_max3_f32 v131, v131, v86, v87
	v_max3_f32 v131, v131, v88, v89
	v_max3_f32 v131, v131, v90, v91
	v_max3_f32 v131, v131, v92, v93
	v_max3_f32 v131, v131, v94, v95
	v_max3_f32 v131, v131, v96, v97
	s_waitcnt lgkmcnt(2)
	v_mfma_f32_32x32x16_bf16 v[18:33], v[136:139], v[216:219], v[18:33]
	v_mov_b32_e32 v132, v131
	s_nop 1
	v_permlane32_swap_b32_e32 v131, v132
	v_max_f32_e32 v132, v132, v132
	v_max_f32_e32 v131, v131, v131
	v_max_f32_e32 v131, v131, v132
	v_sub_f32_e32 v132, v131, v130
	v_cmp_ge_f32_e32 vcc, s60, v132
	v_max_f32_e32 v132, v130, v130
	v_max_f32_e32 v131, v132, v131
	s_waitcnt lgkmcnt(0)
	v_mfma_f32_32x32x16_bf16 v[18:33], v[196:199], v[226:229], v[18:33]
	v_sub_f32_e32 v132, v130, v131
	v_mul_f32_e32 v132, 0x3e0293ee, v132
	v_exp_f32_e32 v132, v132
	s_cmp_eq_u64 vcc, exec
	s_barrier
	s_waitcnt vmcnt(0)
	s_cselect_b64 s[6:7], -1, 0
	s_waitcnt vmcnt(3)
	ds_write_b128 v173, v[192:195] offset:16384
	s_waitcnt vmcnt(2)
	ds_write_b128 v174, v[200:203] offset:16384
	s_waitcnt vmcnt(1)
	ds_write_b128 v175, v[158:161] offset:49152
	s_waitcnt vmcnt(0)
	ds_write_b128 v176, v[204:207] offset:49152
	v_cndmask_b32_e64 v158, v132, 1.0, s[6:7]
	v_cmp_gt_f32_e32 vcc, 1.0, v158
	s_cbranch_vccz .LBB0_1928
	s_and_saveexec_b64 s[54:55], s[4:5]
	ds_write_b32 v168, v158 offset:128
	s_or_b64 exec, exec, s[54:55]
	s_waitcnt lgkmcnt(0)
	v_add_u32_e32 v144, v151, v146
	ds_read_b128 v[132:135], v144 offset:224
	ds_read_b128 v[136:139], v144 offset:192
	ds_read_b128 v[140:143], v144 offset:160
	ds_read_b128 v[160:163], v144 offset:128
	s_waitcnt lgkmcnt(3)
	v_pk_mul_f32 v[14:15], v[14:15], v[132:133]
	s_waitcnt lgkmcnt(2)
	v_pk_mul_f32 v[10:11], v[10:11], v[136:137]
	s_waitcnt lgkmcnt(1)
	v_pk_mul_f32 v[6:7], v[6:7], v[140:141]
	v_pk_mul_f32 v[16:17], v[16:17], v[134:135]
	v_pk_mul_f32 v[12:13], v[12:13], v[138:139]
	v_pk_mul_f32 v[8:9], v[8:9], v[142:143]
	s_waitcnt lgkmcnt(0)
	v_pk_mul_f32 v[4:5], v[4:5], v[162:163]
	v_pk_mul_f32 v[2:3], v[2:3], v[160:161]
	v_pk_mul_f32 v[62:63], v[62:63], v[132:133]
	v_pk_mul_f32 v[58:59], v[58:59], v[136:137]
	v_pk_mul_f32 v[54:55], v[54:55], v[140:141]
	v_pk_mul_f32 v[64:65], v[64:65], v[134:135]
	v_pk_mul_f32 v[60:61], v[60:61], v[138:139]
	v_pk_mul_f32 v[56:57], v[56:57], v[142:143]
	v_pk_mul_f32 v[52:53], v[52:53], v[162:163]
	v_pk_mul_f32 v[50:51], v[50:51], v[160:161]
	v_pk_mul_f32 v[46:47], v[46:47], v[132:133]
	v_pk_mul_f32 v[42:43], v[42:43], v[136:137]
	v_pk_mul_f32 v[38:39], v[38:39], v[140:141]
	v_pk_mul_f32 v[48:49], v[48:49], v[134:135]
	v_pk_mul_f32 v[44:45], v[44:45], v[138:139]
	v_pk_mul_f32 v[40:41], v[40:41], v[142:143]
	v_pk_mul_f32 v[36:37], v[36:37], v[162:163]
	v_pk_mul_f32 v[34:35], v[34:35], v[160:161]
	v_pk_mul_f32 v[30:31], v[30:31], v[132:133]
	v_pk_mul_f32 v[26:27], v[26:27], v[136:137]
	v_pk_mul_f32 v[22:23], v[22:23], v[140:141]
	v_pk_mul_f32 v[32:33], v[32:33], v[134:135]
	v_pk_mul_f32 v[28:29], v[28:29], v[138:139]
	v_pk_mul_f32 v[24:25], v[24:25], v[142:143]
	v_pk_mul_f32 v[20:21], v[20:21], v[162:163]
	v_pk_mul_f32 v[18:19], v[18:19], v[160:161]

; __device__ __forceinline__ void finishSM(f32x16& p0, f32x16& p1, float alpha, float& l_reg, bf16x8& pa0, bf16x8& pa1, bf16x8& pa2, bf16x8& pa3) {
; #pragma unroll
;   for (int r = 0; r < 16; ++r) p1[r] = __builtin_amdgcn_exp2f(p1[r]);
;   float ps = 0;
; #pragma unroll
;   for (int r = 0; r < 16; ++r) ps += p0[r];
; #pragma unroll
;   for (int r = 0; r < 16; ++r) ps += p1[r];
;   { auto rr = __builtin_amdgcn_permlane32_swap(__float_as_uint(ps), __float_as_uint(ps), false, false);
;     ps = __uint_as_float(rr[0]) + __uint_as_float(rr[1]); }
;   l_reg = l_reg * alpha + ps;
;   pack_p(p0, p1, pa0, pa1, pa2, pa3);
; }
.LBB0_1930:
	ds_read_b128 v[66:69], v177 offset:49152
	ds_read_b128 v[70:73], v177 offset:57344
	v_exp_f32_e32 v142, v142
	v_exp_f32_e32 v143, v143
	v_exp_f32_e32 v140, v140
	s_waitcnt lgkmcnt(1)
	v_mfma_f32_32x32x16_bf16 v[82:97], v[66:69], v[126:129], 0
	v_exp_f32_e32 v141, v141
	v_exp_f32_e32 v136, v136
	v_exp_f32_e32 v137, v137
	v_exp_f32_e32 v132, v132
	v_exp_f32_e32 v133, v133
	v_exp_f32_e32 v130, v130
	v_exp_f32_e32 v131, v131
	s_waitcnt lgkmcnt(0)
	v_mfma_f32_32x32x16_bf16 v[66:81], v[70:73], v[126:129], 0
	ds_read_b128 v[126:129], v178 offset:49152
	ds_read_b128 v[152:155], v178 offset:57344
	ds_read_b128 v[174:177], v179 offset:49152
	ds_read_b128 v[188:191], v179 offset:57344
	v_exp_f32_e32 v144, v144
	v_exp_f32_e32 v145, v145
	v_exp_f32_e32 v134, v134
	v_exp_f32_e32 v135, v135
	s_waitcnt lgkmcnt(3)
	v_mfma_f32_32x32x16_bf16 v[82:97], v[126:129], v[122:125], v[82:97]
	ds_read_b128 v[126:129], v180 offset:49152
	ds_read_b128 v[204:207], v180 offset:57344
	ds_read_b128 v[208:211], v181 offset:49152
	ds_read_b128 v[178:181], v181 offset:57344
	ds_read_b128 v[212:215], v182 offset:49152
	ds_read_b128 v[216:219], v182 offset:57344
	ds_read_b128 v[220:223], v183 offset:49152
	ds_read_b128 v[226:229], v183 offset:57344
	s_waitcnt lgkmcnt(10)
	v_mfma_f32_32x32x16_bf16 v[66:81], v[152:155], v[122:125], v[66:81]
	ds_read_b128 v[122:125], v184 offset:49152
	ds_read_b128 v[152:155], v184 offset:57344
	s_waitcnt lgkmcnt(11)
	v_mfma_f32_32x32x16_bf16 v[82:97], v[174:177], v[118:121], v[82:97]
	s_waitcnt lgkmcnt(10)
	v_mfma_f32_32x32x16_bf16 v[66:81], v[188:191], v[118:121], v[66:81]
	v_add_f32_e32 v118, 0, v195
	v_add_f32_e32 v118, v196, v118
	v_add_f32_e32 v118, v197, v118
	v_add_f32_e32 v118, v198, v118
	v_add_f32_e32 v118, v199, v118
	v_add_f32_e32 v118, v201, v118
	v_add_f32_e32 v118, v200, v118
	s_waitcnt lgkmcnt(9)
	v_mfma_f32_32x32x16_bf16 v[82:97], v[126:129], v[114:117], v[82:97]
	v_add_f32_e32 v118, v202, v118
	v_add_f32_e32 v118, v159, v118
	v_add_f32_e32 v118, v160, v118
	v_exp_f32_e32 v120, v138
	v_exp_f32_e32 v121, v139
	v_cvt_pk_bf16_f32 v119, v132, v133
	s_waitcnt lgkmcnt(8)
	v_mfma_f32_32x32x16_bf16 v[66:81], v[204:207], v[114:117], v[66:81]
	v_add_f32_e32 v114, v161, v118
	v_add_f32_e32 v114, v163, v114
	v_add_f32_e32 v114, v162, v114
	v_add_f32_e32 v114, v192, v114
	v_add_f32_e32 v114, v193, v114
	v_add_f32_e32 v114, v194, v114
	v_add_f32_e32 v114, v142, v114
	s_waitcnt lgkmcnt(7)
	v_mfma_f32_32x32x16_bf16 v[82:97], v[208:211], v[110:113], v[82:97]
	v_add_f32_e32 v114, v143, v114
	v_add_f32_e32 v114, v140, v114
	v_add_f32_e32 v114, v141, v114
	v_add_f32_e32 v114, v136, v114
	v_add_f32_e32 v114, v137, v114
	v_add_f32_e32 v114, v132, v114
	v_add_f32_e32 v114, v133, v114
	s_waitcnt lgkmcnt(6)
	v_mfma_f32_32x32x16_bf16 v[66:81], v[178:181], v[110:113], v[66:81]
	v_add_f32_e32 v110, v130, v114
	v_add_f32_e32 v110, v131, v110
	v_add_f32_e32 v110, v144, v110
	v_add_f32_e32 v110, v145, v110
	v_add_f32_e32 v110, v120, v110
	v_add_f32_e32 v110, v121, v110
	v_add_f32_e32 v110, v134, v110
	s_waitcnt lgkmcnt(5)
	v_mfma_f32_32x32x16_bf16 v[82:97], v[212:215], v[106:109], v[82:97]
	v_add_f32_e32 v110, v135, v110
	v_mov_b32_e32 v111, v110
	s_nop 1
	v_permlane32_swap_b32_e32 v110, v111
	v_cvt_pk_bf16_f32 v112, v195, v196
	v_cvt_pk_bf16_f32 v113, v197, v198
	v_cvt_pk_bf16_f32 v114, v199, v201
	s_waitcnt lgkmcnt(4)
	v_mfma_f32_32x32x16_bf16 v[66:81], v[216:219], v[106:109], v[66:81]
	v_cvt_pk_bf16_f32 v115, v200, v202
	v_cvt_pk_bf16_f32 v106, v159, v160
	v_cvt_pk_bf16_f32 v107, v161, v163
	v_cvt_pk_bf16_f32 v108, v162, v192
	v_cvt_pk_bf16_f32 v109, v193, v194
	v_cvt_pk_bf16_f32 v116, v142, v143
	v_cvt_pk_bf16_f32 v117, v140, v141
	s_waitcnt lgkmcnt(3)
	v_mfma_f32_32x32x16_bf16 v[82:97], v[220:223], v[102:105], v[82:97]
	v_cvt_pk_bf16_f32 v118, v136, v137
	v_permlane32_swap_b32_e32 v112, v114
	v_permlane32_swap_b32_e32 v113, v115
	v_permlane32_swap_b32_e32 v106, v108
	s_waitcnt lgkmcnt(2)
	v_mfma_f32_32x32x16_bf16 v[66:81], v[226:229], v[102:105], v[66:81]
	v_cvt_pk_bf16_f32 v102, v130, v131
	v_cvt_pk_bf16_f32 v103, v144, v145
	v_cvt_pk_bf16_f32 v104, v120, v121
	v_cvt_pk_bf16_f32 v105, v134, v135
	v_permlane32_swap_b32_e32 v107, v109
	v_permlane32_swap_b32_e32 v116, v118
	s_waitcnt lgkmcnt(1)
	v_mfma_f32_32x32x16_bf16 v[82:97], v[122:125], v[98:101], v[82:97]
	v_permlane32_swap_b32_e32 v117, v119
	v_permlane32_swap_b32_e32 v102, v104
	v_permlane32_swap_b32_e32 v103, v105
	s_waitcnt lgkmcnt(0)
	v_mfma_f32_32x32x16_bf16 v[66:81], v[152:155], v[98:101], v[66:81]
	ds_read_b64_tr_b16 v[98:99], v172 offset:0
	ds_read_b64_tr_b16 v[100:101], v172 offset:0x800
	ds_read_b64_tr_b16 v[120:121], v172 offset:0x1000
	ds_read_b64_tr_b16 v[122:123], v172 offset:0x1800
	ds_read_b64_tr_b16 v[124:125], v172 offset:0x2000
	ds_read_b64_tr_b16 v[126:127], v172 offset:0x2800
	ds_read_b64_tr_b16 v[128:129], v172 offset:0x3000
	ds_read_b64_tr_b16 v[130:131], v172 offset:0x3800
	s_nop 0
	s_waitcnt lgkmcnt(6)
	v_mfma_f32_32x32x16_bf16 v[2:17], v[112:115], v[98:101], v[2:17]
	ds_read_b64_tr_b16 v[98:99], v172 offset:0x200
	ds_read_b64_tr_b16 v[100:101], v172 offset:0xa00
	s_waitcnt lgkmcnt(6)
	v_mfma_f32_32x32x16_bf16 v[2:17], v[106:109], v[120:123], v[2:17]
	ds_read_b64_tr_b16 v[120:121], v172 offset:0x1200
	ds_read_b64_tr_b16 v[122:123], v172 offset:0x1a00
	s_waitcnt lgkmcnt(6)
	v_mfma_f32_32x32x16_bf16 v[2:17], v[116:119], v[124:127], v[2:17]
	ds_read_b64_tr_b16 v[124:125], v172 offset:0x2200
	ds_read_b64_tr_b16 v[126:127], v172 offset:0x2a00
	ds_read_b64_tr_b16 v[132:133], v172 offset:0x3200
	ds_read_b64_tr_b16 v[134:135], v172 offset:0x3a00
	s_waitcnt lgkmcnt(8)
; #define SBAR() __builtin_amdgcn_sched_barrier(0)
; template <int OFF> __device__ __forceinline__ s16x4 tr_read(int vb) { s16x4 r; asm volatile("ds_read_b64_tr_b16 %0, %1 offset:%2" : "=&v"(r) : "v"(vb), "i"(OFF) : "memory"); return r; }
; template <int D0> __device__ __forceinline__ void pv_one(f32x16& od, int vb, bf16x8 pa0, bf16x8 pa1, bf16x8 pa2, bf16x8 pa3) {
;   const s16x4 l0 = tr_read<v_rd_off(D0, 0, 0)>(vb), h0 = tr_read<v_rd_off(D0, 0, 1)>(vb), l1 = tr_read<v_rd_off(D0, 1, 0)>(vb), h1 = tr_read<v_rd_off(D0, 1, 1)>(vb);
;   const s16x4 l2 = tr_read<v_rd_off(D0, 2, 0)>(vb), h2 = tr_read<v_rd_off(D0, 2, 1)>(vb), l3 = tr_read<v_rd_off(D0, 3, 0)>(vb), h3 = tr_read<v_rd_off(D0, 3, 1)>(vb);
;   asm volatile("s_waitcnt lgkmcnt(0)" ::: "memory"); SBAR();
;     ...
;   od = __builtin_amdgcn_mfma_f32_32x32x16_bf16(pa0, PK(l0, h0), od, 0, 0, 0);
;   od = __builtin_amdgcn_mfma_f32_32x32x16_bf16(pa1, PK(l1, h1), od, 0, 0, 0);
;   od = __builtin_amdgcn_mfma_f32_32x32x16_bf16(pa2, PK(l2, h2), od, 0, 0, 0);
;   od = __builtin_amdgcn_mfma_f32_32x32x16_bf16(pa3, PK(l3, h3), od, 0, 0, 0);
;     ...
; }
; __device__ __forceinline__ void pv_d0(f32x16* o, int vb, bf16x8 pa0, bf16x8 pa1, bf16x8 pa2, bf16x8 pa3) {
;   pv_one<0>(o[0], vb, pa0, pa1, pa2, pa3); pv_one<1>(o[1], vb, pa0, pa1, pa2, pa3); pv_one<2>(o[2], vb, pa0, pa1, pa2, pa3); pv_one<3>(o[3], vb, pa0, pa1, pa2, pa3);
; }
; template <int DQK>
; __device__ __forceinline__ void partialSM(f32x16& p0, f32x16& p1, float& m_reg, float& mn, float& alpha) {
;     ...
;   float pmax = p0[0];
; #pragma unroll
;   for (int r = 1; r < 16; ++r) pmax = fmaxf(pmax, p0[r]);
; #pragma unroll
;   for (int r = 0; r < 16; ++r) pmax = fmaxf(pmax, p1[r]);
;   { auto rr = __builtin_amdgcn_permlane32_swap(__float_as_uint(pmax), __float_as_uint(pmax), false, false);
;     pmax = fmaxf(__uint_as_float(rr[0]), __uint_as_float(rr[1])); }
;   if (__builtin_expect(__all(pmax - m_reg <= THR / SCALE), 1)) { mn = m_reg; alpha = 1.f; }
;   else { mn = fmaxf(m_reg, pmax); alpha = __builtin_amdgcn_exp2f((m_reg - mn) * C); m_reg = mn; }
	v_mfma_f32_32x32x16_bf16 v[2:17], v[102:105], v[128:131], v[2:17]
	s_waitcnt lgkmcnt(6)
	v_mfma_f32_32x32x16_bf16 v[50:65], v[112:115], v[98:101], v[50:65]
	ds_read_b64_tr_b16 v[98:99], v172 offset:0x400
	ds_read_b64_tr_b16 v[100:101], v172 offset:0xc00
	s_waitcnt lgkmcnt(6)
	v_mfma_f32_32x32x16_bf16 v[50:65], v[106:109], v[120:123], v[50:65]
	ds_read_b64_tr_b16 v[120:121], v172 offset:0x1400
	ds_read_b64_tr_b16 v[122:123], v172 offset:0x1c00
	s_waitcnt lgkmcnt(6)
	v_mfma_f32_32x32x16_bf16 v[50:65], v[116:119], v[124:127], v[50:65]
	ds_read_b64_tr_b16 v[124:125], v172 offset:0x2400
	ds_read_b64_tr_b16 v[126:127], v172 offset:0x2c00
	ds_read_b64_tr_b16 v[128:129], v172 offset:0x3400
	ds_read_b64_tr_b16 v[130:131], v172 offset:0x3c00
	s_waitcnt lgkmcnt(8)
	v_mfma_f32_32x32x16_bf16 v[50:65], v[102:105], v[132:135], v[50:65]
	s_waitcnt lgkmcnt(6)
	v_mfma_f32_32x32x16_bf16 v[34:49], v[112:115], v[98:101], v[34:49]
	ds_read_b64_tr_b16 v[98:99], v172 offset:0x600
	ds_read_b64_tr_b16 v[100:101], v172 offset:0xe00
	s_waitcnt lgkmcnt(6)
	v_mfma_f32_32x32x16_bf16 v[34:49], v[106:109], v[120:123], v[34:49]
	ds_read_b64_tr_b16 v[120:121], v172 offset:0x1600
	ds_read_b64_tr_b16 v[122:123], v172 offset:0x1e00
	s_waitcnt lgkmcnt(6)
	v_mfma_f32_32x32x16_bf16 v[34:49], v[116:119], v[124:127], v[34:49]
	ds_read_b64_tr_b16 v[124:125], v172 offset:0x2600
	ds_read_b64_tr_b16 v[126:127], v172 offset:0x2e00
	ds_read_b64_tr_b16 v[132:133], v172 offset:0x3600
	ds_read_b64_tr_b16 v[134:135], v172 offset:0x3e00
	s_waitcnt lgkmcnt(8)
	v_mfma_f32_32x32x16_bf16 v[34:49], v[102:105], v[128:131], v[34:49]
	s_waitcnt lgkmcnt(6)
	v_mfma_f32_32x32x16_bf16 v[18:33], v[112:115], v[98:101], v[18:33]
	v_max_f32_e32 v128, v83, v83
	v_max_f32_e32 v129, v82, v82
	v_max_f32_e32 v128, v129, v128
	v_max3_f32 v128, v128, v84, v85
	v_max3_f32 v128, v128, v86, v87
	v_max3_f32 v98, v128, v88, v89
	v_max3_f32 v98, v98, v90, v91
	v_max3_f32 v98, v98, v92, v93
	s_waitcnt lgkmcnt(4)
	v_mfma_f32_32x32x16_bf16 v[18:33], v[106:109], v[120:123], v[18:33]
	v_max3_f32 v98, v98, v94, v95
	v_max3_f32 v98, v98, v96, v97
	v_max3_f32 v98, v98, v66, v67
	v_max3_f32 v98, v98, v68, v69
	v_max3_f32 v98, v98, v70, v71
	v_max3_f32 v98, v98, v72, v73
	v_max3_f32 v98, v98, v74, v75
	v_max3_f32 v98, v98, v76, v77
	s_waitcnt lgkmcnt(2)
	v_mfma_f32_32x32x16_bf16 v[18:33], v[116:119], v[124:127], v[18:33]
	v_max3_f32 v98, v98, v78, v79
	v_max3_f32 v98, v98, v80, v81
	v_mov_b32_e32 v99, v98
	s_nop 1
	v_permlane32_swap_b32_e32 v98, v99
	v_max_f32_e32 v99, v99, v99
	v_max_f32_e32 v98, v98, v98
	v_max_f32_e32 v98, v98, v99
	v_max_f32_e32 v99, v186, v186
	v_max_f32_e32 v99, v99, v98
	v_sub_f32_e32 v100, v98, v186
	s_waitcnt lgkmcnt(0)
	v_mfma_f32_32x32x16_bf16 v[18:33], v[102:105], v[132:135], v[18:33]
	v_sub_f32_e32 v98, v186, v99
	v_mul_f32_e32 v98, 0x3e0293ee, v98
	v_exp_f32_e32 v98, v98
	v_cmp_ge_f32_e32 vcc, s60, v100
	s_cmp_eq_u64 vcc, exec
	s_cselect_b64 s[6:7], -1, 0
	v_cndmask_b32_e64 v98, v98, 1.0, s[6:7]
	v_cmp_gt_f32_e32 vcc, 1.0, v98
	s_barrier
	s_cbranch_vccz .LBB0_1934
	s_and_saveexec_b64 s[54:55], s[4:5]
	ds_write_b32 v168, v98 offset:128
	s_or_b64 exec, exec, s[54:55]
	s_waitcnt lgkmcnt(0)
	v_add_u32_e32 v108, v151, v146
	ds_read_b128 v[100:103], v108 offset:224
	ds_read_b128 v[104:107], v108 offset:192
	ds_read_b128 v[112:115], v108 offset:160
	ds_read_b128 v[116:119], v108 offset:128
	s_waitcnt lgkmcnt(3)
	v_pk_mul_f32 v[14:15], v[14:15], v[100:101]
	s_waitcnt lgkmcnt(2)
	v_pk_mul_f32 v[10:11], v[10:11], v[104:105]
	s_waitcnt lgkmcnt(1)
	v_pk_mul_f32 v[6:7], v[6:7], v[112:113]
	v_pk_mul_f32 v[16:17], v[16:17], v[102:103]
	v_pk_mul_f32 v[12:13], v[12:13], v[106:107]
	v_pk_mul_f32 v[8:9], v[8:9], v[114:115]
	s_waitcnt lgkmcnt(0)
	v_pk_mul_f32 v[4:5], v[4:5], v[118:119]
	v_pk_mul_f32 v[2:3], v[2:3], v[116:117]
	v_pk_mul_f32 v[62:63], v[62:63], v[100:101]
	v_pk_mul_f32 v[58:59], v[58:59], v[104:105]
	v_pk_mul_f32 v[54:55], v[54:55], v[112:113]
	v_pk_mul_f32 v[64:65], v[64:65], v[102:103]
	v_pk_mul_f32 v[60:61], v[60:61], v[106:107]
	v_pk_mul_f32 v[56:57], v[56:57], v[114:115]
	v_pk_mul_f32 v[52:53], v[52:53], v[118:119]
	v_pk_mul_f32 v[50:51], v[50:51], v[116:117]
	v_pk_mul_f32 v[46:47], v[46:47], v[100:101]
	v_pk_mul_f32 v[42:43], v[42:43], v[104:105]
	v_pk_mul_f32 v[38:39], v[38:39], v[112:113]
	v_pk_mul_f32 v[48:49], v[48:49], v[102:103]
	v_pk_mul_f32 v[44:45], v[44:45], v[106:107]
	v_pk_mul_f32 v[40:41], v[40:41], v[114:115]
	v_pk_mul_f32 v[36:37], v[36:37], v[118:119]
	v_pk_mul_f32 v[34:35], v[34:35], v[116:117]
	v_pk_mul_f32 v[30:31], v[30:31], v[100:101]
	v_pk_mul_f32 v[26:27], v[26:27], v[104:105]
	v_pk_mul_f32 v[22:23], v[22:23], v[112:113]
	v_pk_mul_f32 v[32:33], v[32:33], v[102:103]
	v_pk_mul_f32 v[28:29], v[28:29], v[106:107]
	v_pk_mul_f32 v[24:25], v[24:25], v[114:115]
	v_pk_mul_f32 v[20:21], v[20:21], v[118:119]
	v_pk_mul_f32 v[18:19], v[18:19], v[116:117]
; #define SBAR() __builtin_amdgcn_sched_barrier(0)
; template <int D0> __device__ __forceinline__ void pv_one(f32x16& od, int vb, bf16x8 pa0, bf16x8 pa1, bf16x8 pa2, bf16x8 pa3) {
;   const s16x4 l0 = tr_read<v_rd_off(D0, 0, 0)>(vb), h0 = tr_read<v_rd_off(D0, 0, 1)>(vb), l1 = tr_read<v_rd_off(D0, 1, 0)>(vb), h1 = tr_read<v_rd_off(D0, 1, 1)>(vb);
;   const s16x4 l2 = tr_read<v_rd_off(D0, 2, 0)>(vb), h2 = tr_read<v_rd_off(D0, 2, 1)>(vb), l3 = tr_read<v_rd_off(D0, 3, 0)>(vb), h3 = tr_read<v_rd_off(D0, 3, 1)>(vb);
;   asm volatile("s_waitcnt lgkmcnt(0)" ::: "memory"); SBAR();
;     ...
;   od = __builtin_amdgcn_mfma_f32_32x32x16_bf16(pa0, PK(l0, h0), od, 0, 0, 0);
;   od = __builtin_amdgcn_mfma_f32_32x32x16_bf16(pa1, PK(l1, h1), od, 0, 0, 0);
;   od = __builtin_amdgcn_mfma_f32_32x32x16_bf16(pa2, PK(l2, h2), od, 0, 0, 0);
;   od = __builtin_amdgcn_mfma_f32_32x32x16_bf16(pa3, PK(l3, h3), od, 0, 0, 0);
;     ...
; }
; __device__ __forceinline__ void pv_d0(f32x16* o, int vb, bf16x8 pa0, bf16x8 pa1, bf16x8 pa2, bf16x8 pa3) {
;   pv_one<0>(o[0], vb, pa0, pa1, pa2, pa3); pv_one<1>(o[1], vb, pa0, pa1, pa2, pa3); pv_one<2>(o[2], vb, pa0, pa1, pa2, pa3); pv_one<3>(o[3], vb, pa0, pa1, pa2, pa3);
; }
; template <int DQK>
; __device__ __forceinline__ void partialSM(f32x16& p0, f32x16& p1, float& m_reg, float& mn, float& alpha) {
;     ...
;   const float mnC = -mn * C;
; #pragma unroll
;   for (int r = 0; r < 16; ++r) p0[r] = fmaf(p0[r], C, mnC);
; #pragma unroll
;   for (int r = 0; r < 16; ++r) p1[r] = fmaf(p1[r], C, mnC);
; #pragma unroll
;   for (int r = 0; r < 16; ++r) p0[r] = __builtin_amdgcn_exp2f(p0[r]);
; }
; __device__ __forceinline__ void finishSM(f32x16& p0, f32x16& p1, float alpha, float& l_reg, bf16x8& pa0, bf16x8& pa1, bf16x8& pa2, bf16x8& pa3) {
; #pragma unroll
;   for (int r = 0; r < 16; ++r) p1[r] = __builtin_amdgcn_exp2f(p1[r]);
;   float ps = 0;
; #pragma unroll
;   for (int r = 0; r < 16; ++r) ps += p0[r];
; #pragma unroll
;   for (int r = 0; r < 16; ++r) ps += p1[r];
;   { auto rr = __builtin_amdgcn_permlane32_swap(__float_as_uint(ps), __float_as_uint(ps), false, false);
;     ps = __uint_as_float(rr[0]) + __uint_as_float(rr[1]); }
;   l_reg = l_reg * alpha + ps;
;   pack_p(p0, p1, pa0, pa1, pa2, pa3);
; }
.LBB0_1934:
	v_cndmask_b32_e64 v99, v99, v186, s[6:7]
	v_mul_f32_e32 v99, 0xbe0293ee, v99
	v_fmamk_f32 v82, v82, 0x3e0293ee, v99
	v_fmamk_f32 v83, v83, 0x3e0293ee, v99
	v_fmamk_f32 v108, v95, 0x3e0293ee, v99
	v_fmamk_f32 v95, v76, 0x3e0293ee, v99
	v_exp_f32_e32 v76, v82
	v_fmamk_f32 v84, v84, 0x3e0293ee, v99
	v_fmamk_f32 v109, v96, 0x3e0293ee, v99
	v_fmamk_f32 v96, v77, 0x3e0293ee, v99
	v_exp_f32_e32 v77, v83
	v_fmamk_f32 v85, v85, 0x3e0293ee, v99
	v_fmamk_f32 v112, v97, 0x3e0293ee, v99
	v_fmamk_f32 v97, v78, 0x3e0293ee, v99
	v_exp_f32_e32 v78, v84
	v_fmamk_f32 v86, v86, 0x3e0293ee, v99
	v_fmamk_f32 v66, v66, 0x3e0293ee, v99
	v_exp_f32_e32 v82, v85
	v_fmamk_f32 v100, v87, 0x3e0293ee, v99
	v_fmamk_f32 v101, v88, 0x3e0293ee, v99
	v_fmamk_f32 v102, v89, 0x3e0293ee, v99
	v_fmamk_f32 v103, v90, 0x3e0293ee, v99
	v_fmamk_f32 v104, v91, 0x3e0293ee, v99
	v_fmamk_f32 v105, v92, 0x3e0293ee, v99
	v_fmamk_f32 v106, v93, 0x3e0293ee, v99
	v_fmamk_f32 v107, v94, 0x3e0293ee, v99
	v_fmamk_f32 v67, v67, 0x3e0293ee, v99
	v_fmamk_f32 v87, v68, 0x3e0293ee, v99
	v_fmamk_f32 v88, v69, 0x3e0293ee, v99
	v_fmamk_f32 v89, v70, 0x3e0293ee, v99
	v_fmamk_f32 v90, v71, 0x3e0293ee, v99
	v_fmamk_f32 v91, v72, 0x3e0293ee, v99
	v_fmamk_f32 v92, v73, 0x3e0293ee, v99
	v_fmamk_f32 v93, v74, 0x3e0293ee, v99
	v_fmamk_f32 v94, v75, 0x3e0293ee, v99
	v_exp_f32_e32 v83, v86
	v_fmamk_f32 v79, v79, 0x3e0293ee, v99
	v_fmamk_f32 v80, v80, 0x3e0293ee, v99
	v_fmac_f32_e32 v99, 0x3e0293ee, v81
	v_exp_f32_e32 v81, v66
	v_add_f32_e32 v66, 0, v76
	v_exp_f32_e32 v84, v100
	v_add_f32_e32 v66, v77, v66
	v_exp_f32_e32 v85, v101
	v_add_f32_e32 v66, v78, v66
	v_exp_f32_e32 v86, v102
	v_add_f32_e32 v66, v82, v66
	v_exp_f32_e32 v68, v103
	v_add_f32_e32 v66, v83, v66
	v_exp_f32_e32 v69, v104
	v_add_f32_e32 v66, v84, v66
	v_exp_f32_e32 v70, v105
	v_add_f32_e32 v66, v85, v66
	v_exp_f32_e32 v71, v106
	v_add_f32_e32 v66, v86, v66
	v_exp_f32_e32 v72, v107
	v_add_f32_e32 v66, v68, v66
	v_exp_f32_e32 v73, v108
	v_add_f32_e32 v66, v69, v66
	v_exp_f32_e32 v74, v109
	v_add_f32_e32 v66, v70, v66
	v_exp_f32_e32 v75, v112
	v_add_f32_e32 v66, v71, v66
	v_add_f32_e32 v66, v72, v66
	v_exp_f32_e32 v100, v67
	v_add_f32_e32 v66, v73, v66
	v_exp_f32_e32 v87, v87
	v_add_f32_e32 v66, v74, v66
	v_exp_f32_e32 v88, v88
	v_add_f32_e32 v66, v75, v66
	v_exp_f32_e32 v89, v89
	v_add_f32_e32 v66, v81, v66
	v_exp_f32_e32 v90, v90
	v_add_f32_e32 v66, v100, v66
	v_exp_f32_e32 v91, v91
	v_add_f32_e32 v66, v87, v66
	v_exp_f32_e32 v92, v92
	v_add_f32_e32 v66, v88, v66
	v_exp_f32_e32 v93, v93
	v_add_f32_e32 v66, v89, v66
	v_exp_f32_e32 v94, v94
	v_add_f32_e32 v66, v90, v66
	v_exp_f32_e32 v95, v95
	v_add_f32_e32 v66, v91, v66
	v_exp_f32_e32 v96, v96
	v_add_f32_e32 v66, v92, v66
	v_exp_f32_e32 v97, v97
	v_add_f32_e32 v66, v93, v66
	v_exp_f32_e32 v101, v79
	v_add_f32_e32 v66, v94, v66
	v_exp_f32_e32 v102, v80
	v_add_f32_e32 v66, v95, v66
	v_exp_f32_e32 v99, v99
	v_add_f32_e32 v66, v96, v66
	v_add_f32_e32 v66, v97, v66
	v_add_f32_e32 v66, v101, v66
	v_add_f32_e32 v66, v102, v66
	v_add_f32_e32 v66, v99, v66
	v_mov_b32_e32 v67, v66
	s_nop 1
	v_permlane32_swap_b32_e32 v66, v67
	v_cvt_pk_bf16_f32 v76, v76, v77
	v_cvt_pk_bf16_f32 v77, v78, v82
	v_cvt_pk_bf16_f32 v78, v83, v84
	v_cvt_pk_bf16_f32 v79, v85, v86
	v_cvt_pk_bf16_f32 v68, v68, v69
	v_cvt_pk_bf16_f32 v69, v70, v71
	v_cvt_pk_bf16_f32 v70, v72, v73
	v_cvt_pk_bf16_f32 v71, v74, v75
	v_cvt_pk_bf16_f32 v72, v81, v100
	v_cvt_pk_bf16_f32 v73, v87, v88
	v_cvt_pk_bf16_f32 v74, v89, v90
	v_cvt_pk_bf16_f32 v75, v91, v92
	v_cvt_pk_bf16_f32 v80, v93, v94
	v_cvt_pk_bf16_f32 v81, v95, v96
	v_cvt_pk_bf16_f32 v82, v97, v101
	v_cvt_pk_bf16_f32 v83, v102, v99
	v_permlane32_swap_b32_e32 v76, v78
	v_permlane32_swap_b32_e32 v77, v79
	v_permlane32_swap_b32_e32 v68, v70
	v_permlane32_swap_b32_e32 v69, v71
	v_permlane32_swap_b32_e32 v72, v74
	v_permlane32_swap_b32_e32 v73, v75
	v_permlane32_swap_b32_e32 v80, v82
	v_permlane32_swap_b32_e32 v81, v83
	ds_read_b64_tr_b16 v[84:85], v169 offset:0
	ds_read_b64_tr_b16 v[86:87], v169 offset:0x800
	ds_read_b64_tr_b16 v[88:89], v169 offset:0x1000
	ds_read_b64_tr_b16 v[90:91], v169 offset:0x1800
	ds_read_b64_tr_b16 v[92:93], v169 offset:0x2000
	ds_read_b64_tr_b16 v[94:95], v169 offset:0x2800
	ds_read_b64_tr_b16 v[100:101], v169 offset:0x3000
	ds_read_b64_tr_b16 v[102:103], v169 offset:0x3800
	s_nop 0
	s_waitcnt lgkmcnt(6)
	v_mfma_f32_32x32x16_bf16 v[2:17], v[76:79], v[84:87], v[2:17]
	ds_read_b64_tr_b16 v[84:85], v169 offset:0x200
	ds_read_b64_tr_b16 v[86:87], v169 offset:0xa00
	s_waitcnt lgkmcnt(6)
	v_mfma_f32_32x32x16_bf16 v[2:17], v[68:71], v[88:91], v[2:17]
	ds_read_b64_tr_b16 v[88:89], v169 offset:0x1200
	ds_read_b64_tr_b16 v[90:91], v169 offset:0x1a00
	s_waitcnt lgkmcnt(6)
	v_mfma_f32_32x32x16_bf16 v[2:17], v[72:75], v[92:95], v[2:17]
	ds_read_b64_tr_b16 v[92:93], v169 offset:0x2200
	ds_read_b64_tr_b16 v[94:95], v169 offset:0x2a00
	ds_read_b64_tr_b16 v[104:105], v169 offset:0x3200
	ds_read_b64_tr_b16 v[106:107], v169 offset:0x3a00
	s_waitcnt lgkmcnt(8)
	v_mfma_f32_32x32x16_bf16 v[2:17], v[80:83], v[100:103], v[2:17]
	s_waitcnt lgkmcnt(6)
	v_mfma_f32_32x32x16_bf16 v[50:65], v[76:79], v[84:87], v[50:65]
	ds_read_b64_tr_b16 v[84:85], v169 offset:0x400
	ds_read_b64_tr_b16 v[86:87], v169 offset:0xc00
	s_waitcnt lgkmcnt(6)
	v_mfma_f32_32x32x16_bf16 v[50:65], v[68:71], v[88:91], v[50:65]
	ds_read_b64_tr_b16 v[88:89], v169 offset:0x1400
	ds_read_b64_tr_b16 v[90:91], v169 offset:0x1c00
	s_waitcnt lgkmcnt(6)
	v_mfma_f32_32x32x16_bf16 v[50:65], v[72:75], v[92:95], v[50:65]
	ds_read_b64_tr_b16 v[92:93], v169 offset:0x2400
	ds_read_b64_tr_b16 v[94:95], v169 offset:0x2c00
	ds_read_b64_tr_b16 v[100:101], v169 offset:0x3400
	ds_read_b64_tr_b16 v[102:103], v169 offset:0x3c00
	s_waitcnt lgkmcnt(8)
	v_mfma_f32_32x32x16_bf16 v[50:65], v[80:83], v[104:107], v[50:65]
	s_waitcnt lgkmcnt(6)
	v_mfma_f32_32x32x16_bf16 v[34:49], v[76:79], v[84:87], v[34:49]
	ds_read_b64_tr_b16 v[84:85], v169 offset:0x600
	ds_read_b64_tr_b16 v[86:87], v169 offset:0xe00
	s_waitcnt lgkmcnt(6)
	v_mfma_f32_32x32x16_bf16 v[34:49], v[68:71], v[88:91], v[34:49]
	ds_read_b64_tr_b16 v[88:89], v169 offset:0x1600
	ds_read_b64_tr_b16 v[90:91], v169 offset:0x1e00
	s_waitcnt lgkmcnt(6)
	v_mfma_f32_32x32x16_bf16 v[34:49], v[72:75], v[92:95], v[34:49]
	ds_read_b64_tr_b16 v[92:93], v169 offset:0x2600
	ds_read_b64_tr_b16 v[94:95], v169 offset:0x2e00
	ds_read_b64_tr_b16 v[104:105], v169 offset:0x3600
	ds_read_b64_tr_b16 v[106:107], v169 offset:0x3e00
	s_waitcnt lgkmcnt(8)
	v_mfma_f32_32x32x16_bf16 v[34:49], v[80:83], v[100:103], v[34:49]
	s_waitcnt lgkmcnt(6)
	v_mfma_f32_32x32x16_bf16 v[18:33], v[76:79], v[84:87], v[18:33]
	s_waitcnt lgkmcnt(4)
	v_mfma_f32_32x32x16_bf16 v[18:33], v[68:71], v[88:91], v[18:33]
	s_waitcnt lgkmcnt(2)
	v_mfma_f32_32x32x16_bf16 v[18:33], v[72:75], v[92:95], v[18:33]
	s_waitcnt lgkmcnt(0)
	v_mfma_f32_32x32x16_bf16 v[18:33], v[80:83], v[104:107], v[18:33]
	s_and_saveexec_b64 s[6:7], s[4:5]
	s_cbranch_execz .LBB0_1918
; __device__ __forceinline__ void finishSM(f32x16& p0, f32x16& p1, float alpha, float& l_reg, bf16x8& pa0, bf16x8& pa1, bf16x8& pa2, bf16x8& pa3) {
;     ...
;   { auto rr = __builtin_amdgcn_permlane32_swap(__float_as_uint(ps), __float_as_uint(ps), false, false);
;     ps = __uint_as_float(rr[0]) + __uint_as_float(rr[1]); }
;   l_reg = l_reg * alpha + ps;
; template <int DQK, int MODE, int SDEPTH, int ldq, int ldk, int ldv, int ldo, int ldg> ...
;     ...
;     if (hi == 0) li_l[r32] = l_reg; asm volatile("s_waitcnt lgkmcnt(0)" ::: "memory");
	v_add_f32_e32 v68, v110, v111
	v_fmac_f32_e32 v68, v171, v158
	v_add_f32_e32 v66, v66, v67
	v_fmac_f32_e32 v66, v68, v98
	ds_write_b32 v168, v66
	s_branch .LBB0_1918

; #define SBAR() __builtin_amdgcn_sched_barrier(0)
; template <int OFF> __device__ __forceinline__ s16x4 tr_read(int vb) { s16x4 r; asm volatile("ds_read_b64_tr_b16 %0, %1 offset:%2" : "=&v"(r) : "v"(vb), "i"(OFF) : "memory"); return r; }
; template <int D0> __device__ __forceinline__ void pv_one(f32x16& od, int vb, bf16x8 pa0, bf16x8 pa1, bf16x8 pa2, bf16x8 pa3) {
;   const s16x4 l0 = tr_read<v_rd_off(D0, 0, 0)>(vb), h0 = tr_read<v_rd_off(D0, 0, 1)>(vb), l1 = tr_read<v_rd_off(D0, 1, 0)>(vb), h1 = tr_read<v_rd_off(D0, 1, 1)>(vb);
;   const s16x4 l2 = tr_read<v_rd_off(D0, 2, 0)>(vb), h2 = tr_read<v_rd_off(D0, 2, 1)>(vb), l3 = tr_read<v_rd_off(D0, 3, 0)>(vb), h3 = tr_read<v_rd_off(D0, 3, 1)>(vb);
;   asm volatile("s_waitcnt lgkmcnt(0)" ::: "memory"); SBAR();
;     ...
;   od = __builtin_amdgcn_mfma_f32_32x32x16_bf16(pa0, PK(l0, h0), od, 0, 0, 0);
;   od = __builtin_amdgcn_mfma_f32_32x32x16_bf16(pa1, PK(l1, h1), od, 0, 0, 0);
;   od = __builtin_amdgcn_mfma_f32_32x32x16_bf16(pa2, PK(l2, h2), od, 0, 0, 0);
;   od = __builtin_amdgcn_mfma_f32_32x32x16_bf16(pa3, PK(l3, h3), od, 0, 0, 0);
;     ...
; }
; __device__ __forceinline__ void pv_d0(f32x16* o, int vb, bf16x8 pa0, bf16x8 pa1, bf16x8 pa2, bf16x8 pa3) {
;   pv_one<0>(o[0], vb, pa0, pa1, pa2, pa3); pv_one<1>(o[1], vb, pa0, pa1, pa2, pa3); pv_one<2>(o[2], vb, pa0, pa1, pa2, pa3); pv_one<3>(o[3], vb, pa0, pa1, pa2, pa3);
; }
.LBB0_1968:
	s_lshl_b32 s6, s6, 14
	v_add_u32_e32 v248, s6, v238
	ds_read_b64_tr_b16 v[82:83], v248 offset:0
	ds_read_b64_tr_b16 v[84:85], v248 offset:0x800
	ds_read_b64_tr_b16 v[86:87], v248 offset:0x1000
	ds_read_b64_tr_b16 v[88:89], v248 offset:0x1800
	ds_read_b64_tr_b16 v[90:91], v248 offset:0x2000
	ds_read_b64_tr_b16 v[92:93], v248 offset:0x2800
	ds_read_b64_tr_b16 v[94:95], v248 offset:0x3000
	ds_read_b64_tr_b16 v[96:97], v248 offset:0x3800
	s_nop 0
	s_waitcnt lgkmcnt(6)
	v_mfma_f32_32x32x16_bf16 v[50:65], v[66:69], v[82:85], v[50:65]
	ds_read_b64_tr_b16 v[82:83], v248 offset:0x200
	ds_read_b64_tr_b16 v[84:85], v248 offset:0xa00
	s_waitcnt lgkmcnt(6)
	v_mfma_f32_32x32x16_bf16 v[50:65], v[70:73], v[86:89], v[50:65]
	ds_read_b64_tr_b16 v[86:87], v248 offset:0x1200
	ds_read_b64_tr_b16 v[88:89], v248 offset:0x1a00
	s_waitcnt lgkmcnt(6)
	v_mfma_f32_32x32x16_bf16 v[50:65], v[74:77], v[90:93], v[50:65]
	ds_read_b64_tr_b16 v[90:91], v248 offset:0x2200
	ds_read_b64_tr_b16 v[92:93], v248 offset:0x2a00
	ds_read_b64_tr_b16 v[222:223], v248 offset:0x3200
	ds_read_b64_tr_b16 v[224:225], v248 offset:0x3a00
	s_waitcnt lgkmcnt(8)
	v_mfma_f32_32x32x16_bf16 v[50:65], v[78:81], v[94:97], v[50:65]
	s_waitcnt lgkmcnt(6)
	v_mfma_f32_32x32x16_bf16 v[34:49], v[66:69], v[82:85], v[34:49]
	ds_read_b64_tr_b16 v[82:83], v248 offset:0x400
	ds_read_b64_tr_b16 v[84:85], v248 offset:0xc00
	s_waitcnt lgkmcnt(6)
	v_mfma_f32_32x32x16_bf16 v[34:49], v[70:73], v[86:89], v[34:49]
	ds_read_b64_tr_b16 v[86:87], v248 offset:0x1400
	ds_read_b64_tr_b16 v[88:89], v248 offset:0x1c00
	s_waitcnt lgkmcnt(6)
	v_mfma_f32_32x32x16_bf16 v[34:49], v[74:77], v[90:93], v[34:49]
	ds_read_b64_tr_b16 v[90:91], v248 offset:0x2400
	ds_read_b64_tr_b16 v[92:93], v248 offset:0x2c00
	ds_read_b64_tr_b16 v[94:95], v248 offset:0x3400
	ds_read_b64_tr_b16 v[96:97], v248 offset:0x3c00
	s_waitcnt lgkmcnt(8)
	v_mfma_f32_32x32x16_bf16 v[34:49], v[78:81], v[222:225], v[34:49]
	s_waitcnt lgkmcnt(6)
	v_mfma_f32_32x32x16_bf16 v[18:33], v[66:69], v[82:85], v[18:33]
	ds_read_b64_tr_b16 v[82:83], v248 offset:0x600
	ds_read_b64_tr_b16 v[84:85], v248 offset:0xe00
	s_waitcnt lgkmcnt(6)
	v_mfma_f32_32x32x16_bf16 v[18:33], v[70:73], v[86:89], v[18:33]
	ds_read_b64_tr_b16 v[86:87], v248 offset:0x1600
	ds_read_b64_tr_b16 v[88:89], v248 offset:0x1e00
	s_waitcnt lgkmcnt(6)
	v_mfma_f32_32x32x16_bf16 v[18:33], v[74:77], v[90:93], v[18:33]
	ds_read_b64_tr_b16 v[90:91], v248 offset:0x2600
	ds_read_b64_tr_b16 v[92:93], v248 offset:0x2e00
	ds_read_b64_tr_b16 v[222:223], v248 offset:0x3600
	ds_read_b64_tr_b16 v[224:225], v248 offset:0x3e00
	s_waitcnt lgkmcnt(8)
	v_mfma_f32_32x32x16_bf16 v[18:33], v[78:81], v[94:97], v[18:33]
	s_waitcnt lgkmcnt(6)
	v_mfma_f32_32x32x16_bf16 v[2:17], v[66:69], v[82:85], v[2:17]
	s_andn2_b64 vcc, exec, s[60:61]
	s_waitcnt lgkmcnt(4)
	v_mfma_f32_32x32x16_bf16 v[2:17], v[70:73], v[86:89], v[2:17]
	s_waitcnt lgkmcnt(2)
	v_mfma_f32_32x32x16_bf16 v[2:17], v[74:77], v[90:93], v[2:17]
	s_waitcnt lgkmcnt(0)
	v_mfma_f32_32x32x16_bf16 v[2:17], v[78:81], v[222:225], v[2:17]
	s_cbranch_vccnz .LBB0_1954
	s_xor_b32 s6, s6, 0x4000
	s_waitcnt vmcnt(0)
	s_add_i32 s6, s6, 0
	v_add_u32_e32 v66, s6, v231
	s_waitcnt vmcnt(1)
	ds_write_b128 v66, v[106:109]
	v_add_u32_e32 v66, s6, v232
	s_cmp_gt_u32 s74, 2
	s_waitcnt vmcnt(0)
	ds_write_b128 v66, v[142:145]
	s_cbranch_scc1 .LBB0_1954
	v_add_u32_e32 v67, s6, v236
	v_add_u32_e32 v66, s6, v237
	ds_write_b128 v67, v[102:105] offset:32768
	ds_write_b128 v66, v[134:137] offset:32768
	s_branch .LBB0_1954
